# rope epilogues of phase 8 (k_rope) and phase 9 (q_rope) load their cos/sin pairs in batches of 16 instead of 64 serial round trips; gk_low GEMV and decay product loads batched
# speedup vs baseline: 1.1062x; 1.0193x over previous
.LBB0_60:
	s_and_b64 vcc, exec, s[0:1]
	s_cbranch_vccz .LBB0_88
	v_readlane_b32 s0, v254, 6
	v_readlane_b32 s1, v254, 7
	v_readfirstlane_b32 s12, v184
	v_readfirstlane_b32 s13, v185
	s_andn2_b64 vcc, exec, s[0:1]
	s_cbranch_vccnz .LBB0_88
	s_cmpk_lg_i32 s64, 0x200
	s_cbranch_scc1 .Lp9_setup
	s_cmpk_lt_i32 s50, 0x120
	s_cbranch_scc0 .Lp9_setup
	s_mov_b32 s14, s12
	s_mov_b32 s15, s13
	s_add_u32 s16, s14, 0x4000000
	s_addc_u32 s17, s15, 0
	s_add_u32 s18, s14, 0x2100000
	s_addc_u32 s19, s15, 0
	s_add_u32 s20, s14, 0x1000000
	s_addc_u32 s21, s15, 0
	s_add_u32 s22, s14, 0x3e00000
	s_addc_u32 s23, s15, 0
	s_add_i32 s5, s50, 0x200
	s_lshl_b32 s4, s5, 8
	s_mov_b32 s100, 1
	s_branch .LBB0_95

.Lp9_setup:
	s_add_u32 s14, s12, 0x800000
	s_addc_u32 s15, s13, 0
	s_add_u32 s16, s12, 0x2e00000
	s_addc_u32 s17, s13, 0
	s_add_u32 s18, s12, 0x3100000
	s_addc_u32 s19, s13, 0
	s_add_u32 s20, s12, 0x3e00000
	s_addc_u32 s21, s13, 0
	s_add_u32 s22, s12, 0x8000000
	s_addc_u32 s23, s13, 0
	s_add_u32 s4, s12, 0xb000000
	s_addc_u32 s5, s13, 0
	s_add_u32 s6, s12, 0xd000000
	s_addc_u32 s7, s13, 0
	s_mov_b32 s8, s50
	s_mov_b32 s101, s64
	s_movk_i32 s32, 0x6ff
	s_cmpk_lg_i32 s64, 0x200
	s_cbranch_scc1 .Lp9_go
	s_movk_i32 s101, 0x120
	s_movk_i32 s32, 0x23f
	s_cmpk_lt_i32 s50, 0x120
	s_cbranch_scc1 .Lp9_go
	s_add_i32 s8, s50, 0x120
	s_movk_i32 s101, 0xe0
	s_movk_i32 s32, 0x6ff

.LBB0_86:
	s_andn2_saveexec_b64 s[2:3], s[0:1]
	s_cbranch_execz .LBB0_63
	v_lshlrev_b32_e32 v132, 8, v130
	v_lshl_add_u32 v132, v217, 2, v132
	v_mov_b32_e32 v133, 0
	v_lshl_add_u64 v[132:133], s[20:21], 0, v[132:133]
	v_lshl_add_u64 v[134:135], v[128:129], 0, v[130:131]
	v_mov_b64_e32 v[136:137], s[22:23]
	v_mad_u64_u32 v[138:139], s[0:1], v134, s33, v[136:137]
	v_mad_i32_i24 v139, v135, s33, v139
	v_lshl_add_u64 v[138:139], v[138:139], 0, v[186:187]
	v_add_co_u32_e32 v140, vcc, 0x0, v132
	s_nop 1
	v_addc_co_u32_e32 v141, vcc, 0, v133, vcc
	v_add_co_u32_e32 v142, vcc, 0x1000, v132
	s_nop 1
	v_addc_co_u32_e32 v143, vcc, 0, v133, vcc
	ds_read_b128 v[144:147], v216 offset:49152
	ds_read_b128 v[148:151], v216 offset:49184
	ds_read_b128 v[152:155], v216 offset:49216
	ds_read_b128 v[156:159], v216 offset:49248
	global_load_dword v160, v[140:141], off
	global_load_dword v161, v[140:141], off offset:128
	global_load_dword v162, v[140:141], off offset:256
	global_load_dword v163, v[140:141], off offset:384
	global_load_dword v164, v[140:141], off offset:512
	global_load_dword v165, v[140:141], off offset:640
	global_load_dword v166, v[140:141], off offset:768
	global_load_dword v167, v[140:141], off offset:896
	global_load_dword v168, v[140:141], off offset:2048
	global_load_dword v169, v[140:141], off offset:2176
	global_load_dword v170, v[140:141], off offset:2304
	global_load_dword v171, v[140:141], off offset:2432
	global_load_dword v172, v[140:141], off offset:2560
	global_load_dword v173, v[140:141], off offset:2688
	global_load_dword v174, v[140:141], off offset:2816
	global_load_dword v175, v[140:141], off offset:2944
	global_load_dword v176, v[142:143], off
	global_load_dword v177, v[142:143], off offset:128
	global_load_dword v178, v[142:143], off offset:256
	global_load_dword v179, v[142:143], off offset:384
	global_load_dword v180, v[142:143], off offset:512
	global_load_dword v181, v[142:143], off offset:640
	global_load_dword v182, v[142:143], off offset:768
	global_load_dword v183, v[142:143], off offset:896
	global_load_dword v204, v[142:143], off offset:2048
	global_load_dword v205, v[142:143], off offset:2176
	global_load_dword v206, v[142:143], off offset:2304
	global_load_dword v207, v[142:143], off offset:2432
	global_load_dword v208, v[142:143], off offset:2560
	global_load_dword v209, v[142:143], off offset:2688
	global_load_dword v210, v[142:143], off offset:2816
	global_load_dword v211, v[142:143], off offset:2944
	v_mov_b64_e32 v[192:193], v[138:139]
	v_add_co_u32_e32 v194, vcc, 0xc00, v138
	s_nop 1
	v_addc_co_u32_e32 v195, vcc, 0, v139, vcc
	v_add_co_u32_e32 v196, vcc, 0x1800, v138
	s_nop 1
	v_addc_co_u32_e32 v197, vcc, 0, v139, vcc
	v_add_co_u32_e32 v198, vcc, 0x2400, v138
	s_nop 1
	v_addc_co_u32_e32 v199, vcc, 0, v139, vcc
	s_waitcnt lgkmcnt(0)
	v_mul_f32_e32 v200, 0x3dd53b94, v144
	v_mul_f32_e32 v112, v112, v200
	v_mul_f32_e32 v96, v96, v200
	s_waitcnt vmcnt(30)
	v_mul_f32_e32 v201, v96, v161
	v_fma_f32 v201, v160, v112, -v201
	v_mul_f32_e32 v202, v112, v161
	v_fmac_f32_e32 v202, v160, v96
	v_cvt_pk_bf16_f32 v201, v201, s0
	v_cvt_pk_bf16_f32 v202, v202, s0
	global_store_short v[192:193], v201, off offset:256
	global_store_short v[192:193], v202, off offset:320
	v_mul_f32_e32 v200, 0x3dd53b94, v145
	v_mul_f32_e32 v113, v113, v200
	v_mul_f32_e32 v97, v97, v200
	s_waitcnt vmcnt(30)
	v_mul_f32_e32 v201, v97, v163
	v_fma_f32 v201, v162, v113, -v201
	v_mul_f32_e32 v202, v113, v163
	v_fmac_f32_e32 v202, v162, v97
	v_cvt_pk_bf16_f32 v201, v201, s0
	v_cvt_pk_bf16_f32 v202, v202, s0
	global_store_short v[192:193], v201, off offset:640
	global_store_short v[192:193], v202, off offset:704
	v_mul_f32_e32 v200, 0x3dd53b94, v146
	v_mul_f32_e32 v114, v114, v200
	v_mul_f32_e32 v98, v98, v200
	s_waitcnt vmcnt(30)
	v_mul_f32_e32 v201, v98, v165
	v_fma_f32 v201, v164, v114, -v201
	v_mul_f32_e32 v202, v114, v165
	v_fmac_f32_e32 v202, v164, v98
	v_cvt_pk_bf16_f32 v201, v201, s0
	v_cvt_pk_bf16_f32 v202, v202, s0
	global_store_short v[192:193], v201, off offset:1024
	global_store_short v[192:193], v202, off offset:1088
	v_mul_f32_e32 v200, 0x3dd53b94, v147
	v_mul_f32_e32 v115, v115, v200
	v_mul_f32_e32 v99, v99, v200
	s_waitcnt vmcnt(30)
	v_mul_f32_e32 v201, v99, v167
	v_fma_f32 v201, v166, v115, -v201
	v_mul_f32_e32 v202, v115, v167
	v_fmac_f32_e32 v202, v166, v99
	v_cvt_pk_bf16_f32 v201, v201, s0
	v_cvt_pk_bf16_f32 v202, v202, s0
	global_store_short v[192:193], v201, off offset:1408
	global_store_short v[192:193], v202, off offset:1472
	v_mul_f32_e32 v200, 0x3dd53b94, v148
	v_mul_f32_e32 v116, v116, v200
	v_mul_f32_e32 v100, v100, v200
	s_waitcnt vmcnt(30)
	v_mul_f32_e32 v201, v100, v169
	v_fma_f32 v201, v168, v116, -v201
	v_mul_f32_e32 v202, v116, v169
	v_fmac_f32_e32 v202, v168, v100
	v_cvt_pk_bf16_f32 v201, v201, s0
	v_cvt_pk_bf16_f32 v202, v202, s0
	global_store_short v[194:195], v201, off offset:256
	global_store_short v[194:195], v202, off offset:320
	v_mul_f32_e32 v200, 0x3dd53b94, v149
	v_mul_f32_e32 v117, v117, v200
	v_mul_f32_e32 v101, v101, v200
	s_waitcnt vmcnt(30)
	v_mul_f32_e32 v201, v101, v171
	v_fma_f32 v201, v170, v117, -v201
	v_mul_f32_e32 v202, v117, v171
	v_fmac_f32_e32 v202, v170, v101
	v_cvt_pk_bf16_f32 v201, v201, s0
	v_cvt_pk_bf16_f32 v202, v202, s0
	global_store_short v[194:195], v201, off offset:640
	global_store_short v[194:195], v202, off offset:704
	v_mul_f32_e32 v200, 0x3dd53b94, v150
	v_mul_f32_e32 v118, v118, v200
	v_mul_f32_e32 v102, v102, v200
	s_waitcnt vmcnt(30)
	v_mul_f32_e32 v201, v102, v173
	v_fma_f32 v201, v172, v118, -v201
	v_mul_f32_e32 v202, v118, v173
	v_fmac_f32_e32 v202, v172, v102
	v_cvt_pk_bf16_f32 v201, v201, s0
	v_cvt_pk_bf16_f32 v202, v202, s0
	global_store_short v[194:195], v201, off offset:1024
	global_store_short v[194:195], v202, off offset:1088
	v_mul_f32_e32 v200, 0x3dd53b94, v151
	v_mul_f32_e32 v119, v119, v200
	v_mul_f32_e32 v103, v103, v200
	s_waitcnt vmcnt(30)
	v_mul_f32_e32 v201, v103, v175
	v_fma_f32 v201, v174, v119, -v201
	v_mul_f32_e32 v202, v119, v175
	v_fmac_f32_e32 v202, v174, v103
	v_cvt_pk_bf16_f32 v201, v201, s0
	v_cvt_pk_bf16_f32 v202, v202, s0
	global_store_short v[194:195], v201, off offset:1408
	global_store_short v[194:195], v202, off offset:1472
	v_mul_f32_e32 v200, 0x3dd53b94, v152
	v_mul_f32_e32 v120, v120, v200
	v_mul_f32_e32 v104, v104, v200
	s_waitcnt vmcnt(30)
	v_mul_f32_e32 v201, v104, v177
	v_fma_f32 v201, v176, v120, -v201
	v_mul_f32_e32 v202, v120, v177
	v_fmac_f32_e32 v202, v176, v104
	v_cvt_pk_bf16_f32 v201, v201, s0
	v_cvt_pk_bf16_f32 v202, v202, s0
	global_store_short v[196:197], v201, off offset:256
	global_store_short v[196:197], v202, off offset:320
	v_mul_f32_e32 v200, 0x3dd53b94, v153
	v_mul_f32_e32 v121, v121, v200
	v_mul_f32_e32 v105, v105, v200
	s_waitcnt vmcnt(30)
	v_mul_f32_e32 v201, v105, v179
	v_fma_f32 v201, v178, v121, -v201
	v_mul_f32_e32 v202, v121, v179
	v_fmac_f32_e32 v202, v178, v105
	v_cvt_pk_bf16_f32 v201, v201, s0
	v_cvt_pk_bf16_f32 v202, v202, s0
	global_store_short v[196:197], v201, off offset:640
	global_store_short v[196:197], v202, off offset:704
	v_mul_f32_e32 v200, 0x3dd53b94, v154
	v_mul_f32_e32 v122, v122, v200
	v_mul_f32_e32 v106, v106, v200
	s_waitcnt vmcnt(30)
	v_mul_f32_e32 v201, v106, v181
	v_fma_f32 v201, v180, v122, -v201
	v_mul_f32_e32 v202, v122, v181
	v_fmac_f32_e32 v202, v180, v106
	v_cvt_pk_bf16_f32 v201, v201, s0
	v_cvt_pk_bf16_f32 v202, v202, s0
	global_store_short v[196:197], v201, off offset:1024
	global_store_short v[196:197], v202, off offset:1088
	v_mul_f32_e32 v200, 0x3dd53b94, v155
	v_mul_f32_e32 v123, v123, v200
	v_mul_f32_e32 v107, v107, v200
	s_waitcnt vmcnt(30)
	v_mul_f32_e32 v201, v107, v183
	v_fma_f32 v201, v182, v123, -v201
	v_mul_f32_e32 v202, v123, v183
	v_fmac_f32_e32 v202, v182, v107
	v_cvt_pk_bf16_f32 v201, v201, s0
	v_cvt_pk_bf16_f32 v202, v202, s0
	global_store_short v[196:197], v201, off offset:1408
	global_store_short v[196:197], v202, off offset:1472
	v_mul_f32_e32 v200, 0x3dd53b94, v156
	v_mul_f32_e32 v124, v124, v200
	v_mul_f32_e32 v108, v108, v200
	s_waitcnt vmcnt(30)
	v_mul_f32_e32 v201, v108, v205
	v_fma_f32 v201, v204, v124, -v201
	v_mul_f32_e32 v202, v124, v205
	v_fmac_f32_e32 v202, v204, v108
	v_cvt_pk_bf16_f32 v201, v201, s0
	v_cvt_pk_bf16_f32 v202, v202, s0
	global_store_short v[198:199], v201, off offset:256
	global_store_short v[198:199], v202, off offset:320
	v_mul_f32_e32 v200, 0x3dd53b94, v157
	v_mul_f32_e32 v125, v125, v200
	v_mul_f32_e32 v109, v109, v200
	s_waitcnt vmcnt(30)
	v_mul_f32_e32 v201, v109, v207
	v_fma_f32 v201, v206, v125, -v201
	v_mul_f32_e32 v202, v125, v207
	v_fmac_f32_e32 v202, v206, v109
	v_cvt_pk_bf16_f32 v201, v201, s0
	v_cvt_pk_bf16_f32 v202, v202, s0
	global_store_short v[198:199], v201, off offset:640
	global_store_short v[198:199], v202, off offset:704
	v_mul_f32_e32 v200, 0x3dd53b94, v158
	v_mul_f32_e32 v126, v126, v200
	v_mul_f32_e32 v110, v110, v200
	s_waitcnt vmcnt(30)
	v_mul_f32_e32 v201, v110, v209
	v_fma_f32 v201, v208, v126, -v201
	v_mul_f32_e32 v202, v126, v209
	v_fmac_f32_e32 v202, v208, v110
	v_cvt_pk_bf16_f32 v201, v201, s0
	v_cvt_pk_bf16_f32 v202, v202, s0
	global_store_short v[198:199], v201, off offset:1024
	global_store_short v[198:199], v202, off offset:1088
	v_mul_f32_e32 v200, 0x3dd53b94, v159
	v_mul_f32_e32 v127, v127, v200
	v_mul_f32_e32 v111, v111, v200
	s_waitcnt vmcnt(30)
	v_mul_f32_e32 v201, v111, v211
	v_fma_f32 v201, v210, v127, -v201
	v_mul_f32_e32 v202, v127, v211
	v_fmac_f32_e32 v202, v210, v111
	v_cvt_pk_bf16_f32 v201, v201, s0
	v_cvt_pk_bf16_f32 v202, v202, s0
	global_store_short v[198:199], v201, off offset:1408
	global_store_short v[198:199], v202, off offset:1472
	v_add_co_u32_e32 v140, vcc, 0x2000, v132
	s_nop 1
	v_addc_co_u32_e32 v141, vcc, 0, v133, vcc
	v_add_co_u32_e32 v142, vcc, 0x3000, v132
	s_nop 1
	v_addc_co_u32_e32 v143, vcc, 0, v133, vcc
	ds_read_b128 v[144:147], v216 offset:49280
	ds_read_b128 v[148:151], v216 offset:49312
	ds_read_b128 v[152:155], v216 offset:49344
	ds_read_b128 v[156:159], v216 offset:49376
	global_load_dword v160, v[140:141], off
	global_load_dword v161, v[140:141], off offset:128
	global_load_dword v162, v[140:141], off offset:256
	global_load_dword v163, v[140:141], off offset:384
	global_load_dword v164, v[140:141], off offset:512
	global_load_dword v165, v[140:141], off offset:640
	global_load_dword v166, v[140:141], off offset:768
	global_load_dword v167, v[140:141], off offset:896
	global_load_dword v168, v[140:141], off offset:2048
	global_load_dword v169, v[140:141], off offset:2176
	global_load_dword v170, v[140:141], off offset:2304
	global_load_dword v171, v[140:141], off offset:2432
	global_load_dword v172, v[140:141], off offset:2560
	global_load_dword v173, v[140:141], off offset:2688
	global_load_dword v174, v[140:141], off offset:2816
	global_load_dword v175, v[140:141], off offset:2944
	global_load_dword v176, v[142:143], off
	global_load_dword v177, v[142:143], off offset:128
	global_load_dword v178, v[142:143], off offset:256
	global_load_dword v179, v[142:143], off offset:384
	global_load_dword v180, v[142:143], off offset:512
	global_load_dword v181, v[142:143], off offset:640
	global_load_dword v182, v[142:143], off offset:768
	global_load_dword v183, v[142:143], off offset:896
	global_load_dword v204, v[142:143], off offset:2048
	global_load_dword v205, v[142:143], off offset:2176
	global_load_dword v206, v[142:143], off offset:2304
	global_load_dword v207, v[142:143], off offset:2432
	global_load_dword v208, v[142:143], off offset:2560
	global_load_dword v209, v[142:143], off offset:2688
	global_load_dword v210, v[142:143], off offset:2816
	global_load_dword v211, v[142:143], off offset:2944
	v_add_co_u32_e32 v192, vcc, 0x3000, v138
	s_nop 1
	v_addc_co_u32_e32 v193, vcc, 0, v139, vcc
	v_add_co_u32_e32 v194, vcc, 0x3c00, v138
	s_nop 1
	v_addc_co_u32_e32 v195, vcc, 0, v139, vcc
	v_add_co_u32_e32 v196, vcc, 0x4800, v138
	s_nop 1
	v_addc_co_u32_e32 v197, vcc, 0, v139, vcc
	v_add_co_u32_e32 v198, vcc, 0x5400, v138
	s_nop 1
	v_addc_co_u32_e32 v199, vcc, 0, v139, vcc
	s_waitcnt lgkmcnt(0)
	v_mul_f32_e32 v200, 0x3dd53b94, v144
	v_mul_f32_e32 v80, v80, v200
	v_mul_f32_e32 v64, v64, v200
	s_waitcnt vmcnt(30)
	v_mul_f32_e32 v201, v64, v161
	v_fma_f32 v201, v160, v80, -v201
	v_mul_f32_e32 v202, v80, v161
	v_fmac_f32_e32 v202, v160, v64
	v_cvt_pk_bf16_f32 v201, v201, s0
	v_cvt_pk_bf16_f32 v202, v202, s0
	global_store_short v[192:193], v201, off offset:256
	global_store_short v[192:193], v202, off offset:320
	v_mul_f32_e32 v200, 0x3dd53b94, v145
	v_mul_f32_e32 v81, v81, v200
	v_mul_f32_e32 v65, v65, v200
	s_waitcnt vmcnt(30)
	v_mul_f32_e32 v201, v65, v163
	v_fma_f32 v201, v162, v81, -v201
	v_mul_f32_e32 v202, v81, v163
	v_fmac_f32_e32 v202, v162, v65
	v_cvt_pk_bf16_f32 v201, v201, s0
	v_cvt_pk_bf16_f32 v202, v202, s0
	global_store_short v[192:193], v201, off offset:640
	global_store_short v[192:193], v202, off offset:704
	v_mul_f32_e32 v200, 0x3dd53b94, v146
	v_mul_f32_e32 v82, v82, v200
	v_mul_f32_e32 v66, v66, v200
	s_waitcnt vmcnt(30)
	v_mul_f32_e32 v201, v66, v165
	v_fma_f32 v201, v164, v82, -v201
	v_mul_f32_e32 v202, v82, v165
	v_fmac_f32_e32 v202, v164, v66
	v_cvt_pk_bf16_f32 v201, v201, s0
	v_cvt_pk_bf16_f32 v202, v202, s0
	global_store_short v[192:193], v201, off offset:1024
	global_store_short v[192:193], v202, off offset:1088
	v_mul_f32_e32 v200, 0x3dd53b94, v147
	v_mul_f32_e32 v83, v83, v200
	v_mul_f32_e32 v67, v67, v200
	s_waitcnt vmcnt(30)
	v_mul_f32_e32 v201, v67, v167
	v_fma_f32 v201, v166, v83, -v201
	v_mul_f32_e32 v202, v83, v167
	v_fmac_f32_e32 v202, v166, v67
	v_cvt_pk_bf16_f32 v201, v201, s0
	v_cvt_pk_bf16_f32 v202, v202, s0
	global_store_short v[192:193], v201, off offset:1408
	global_store_short v[192:193], v202, off offset:1472
	v_mul_f32_e32 v200, 0x3dd53b94, v148
	v_mul_f32_e32 v84, v84, v200
	v_mul_f32_e32 v68, v68, v200
	s_waitcnt vmcnt(30)
	v_mul_f32_e32 v201, v68, v169
	v_fma_f32 v201, v168, v84, -v201
	v_mul_f32_e32 v202, v84, v169
	v_fmac_f32_e32 v202, v168, v68
	v_cvt_pk_bf16_f32 v201, v201, s0
	v_cvt_pk_bf16_f32 v202, v202, s0
	global_store_short v[194:195], v201, off offset:256
	global_store_short v[194:195], v202, off offset:320
	v_mul_f32_e32 v200, 0x3dd53b94, v149
	v_mul_f32_e32 v85, v85, v200
	v_mul_f32_e32 v69, v69, v200
	s_waitcnt vmcnt(30)
	v_mul_f32_e32 v201, v69, v171
	v_fma_f32 v201, v170, v85, -v201
	v_mul_f32_e32 v202, v85, v171
	v_fmac_f32_e32 v202, v170, v69
	v_cvt_pk_bf16_f32 v201, v201, s0
	v_cvt_pk_bf16_f32 v202, v202, s0
	global_store_short v[194:195], v201, off offset:640
	global_store_short v[194:195], v202, off offset:704
	v_mul_f32_e32 v200, 0x3dd53b94, v150
	v_mul_f32_e32 v86, v86, v200
	v_mul_f32_e32 v70, v70, v200
	s_waitcnt vmcnt(30)
	v_mul_f32_e32 v201, v70, v173
	v_fma_f32 v201, v172, v86, -v201
	v_mul_f32_e32 v202, v86, v173
	v_fmac_f32_e32 v202, v172, v70
	v_cvt_pk_bf16_f32 v201, v201, s0
	v_cvt_pk_bf16_f32 v202, v202, s0
	global_store_short v[194:195], v201, off offset:1024
	global_store_short v[194:195], v202, off offset:1088
	v_mul_f32_e32 v200, 0x3dd53b94, v151
	v_mul_f32_e32 v87, v87, v200
	v_mul_f32_e32 v71, v71, v200
	s_waitcnt vmcnt(30)
	v_mul_f32_e32 v201, v71, v175
	v_fma_f32 v201, v174, v87, -v201
	v_mul_f32_e32 v202, v87, v175
	v_fmac_f32_e32 v202, v174, v71
	v_cvt_pk_bf16_f32 v201, v201, s0
	v_cvt_pk_bf16_f32 v202, v202, s0
	global_store_short v[194:195], v201, off offset:1408
	global_store_short v[194:195], v202, off offset:1472
	v_mul_f32_e32 v200, 0x3dd53b94, v152
	v_mul_f32_e32 v88, v88, v200
	v_mul_f32_e32 v72, v72, v200
	s_waitcnt vmcnt(30)
	v_mul_f32_e32 v201, v72, v177
	v_fma_f32 v201, v176, v88, -v201
	v_mul_f32_e32 v202, v88, v177
	v_fmac_f32_e32 v202, v176, v72
	v_cvt_pk_bf16_f32 v201, v201, s0
	v_cvt_pk_bf16_f32 v202, v202, s0
	global_store_short v[196:197], v201, off offset:256
	global_store_short v[196:197], v202, off offset:320
	v_mul_f32_e32 v200, 0x3dd53b94, v153
	v_mul_f32_e32 v89, v89, v200
	v_mul_f32_e32 v73, v73, v200
	s_waitcnt vmcnt(30)
	v_mul_f32_e32 v201, v73, v179
	v_fma_f32 v201, v178, v89, -v201
	v_mul_f32_e32 v202, v89, v179
	v_fmac_f32_e32 v202, v178, v73
	v_cvt_pk_bf16_f32 v201, v201, s0
	v_cvt_pk_bf16_f32 v202, v202, s0
	global_store_short v[196:197], v201, off offset:640
	global_store_short v[196:197], v202, off offset:704
	v_mul_f32_e32 v200, 0x3dd53b94, v154
	v_mul_f32_e32 v90, v90, v200
	v_mul_f32_e32 v74, v74, v200
	s_waitcnt vmcnt(30)
	v_mul_f32_e32 v201, v74, v181
	v_fma_f32 v201, v180, v90, -v201
	v_mul_f32_e32 v202, v90, v181
	v_fmac_f32_e32 v202, v180, v74
	v_cvt_pk_bf16_f32 v201, v201, s0
	v_cvt_pk_bf16_f32 v202, v202, s0
	global_store_short v[196:197], v201, off offset:1024
	global_store_short v[196:197], v202, off offset:1088
	v_mul_f32_e32 v200, 0x3dd53b94, v155
	v_mul_f32_e32 v91, v91, v200
	v_mul_f32_e32 v75, v75, v200
	s_waitcnt vmcnt(30)
	v_mul_f32_e32 v201, v75, v183
	v_fma_f32 v201, v182, v91, -v201
	v_mul_f32_e32 v202, v91, v183
	v_fmac_f32_e32 v202, v182, v75
	v_cvt_pk_bf16_f32 v201, v201, s0
	v_cvt_pk_bf16_f32 v202, v202, s0
	global_store_short v[196:197], v201, off offset:1408
	global_store_short v[196:197], v202, off offset:1472
	v_mul_f32_e32 v200, 0x3dd53b94, v156
	v_mul_f32_e32 v92, v92, v200
	v_mul_f32_e32 v76, v76, v200
	s_waitcnt vmcnt(30)
	v_mul_f32_e32 v201, v76, v205
	v_fma_f32 v201, v204, v92, -v201
	v_mul_f32_e32 v202, v92, v205
	v_fmac_f32_e32 v202, v204, v76
	v_cvt_pk_bf16_f32 v201, v201, s0
	v_cvt_pk_bf16_f32 v202, v202, s0
	global_store_short v[198:199], v201, off offset:256
	global_store_short v[198:199], v202, off offset:320
	v_mul_f32_e32 v200, 0x3dd53b94, v157
	v_mul_f32_e32 v93, v93, v200
	v_mul_f32_e32 v77, v77, v200
	s_waitcnt vmcnt(30)
	v_mul_f32_e32 v201, v77, v207
	v_fma_f32 v201, v206, v93, -v201
	v_mul_f32_e32 v202, v93, v207
	v_fmac_f32_e32 v202, v206, v77
	v_cvt_pk_bf16_f32 v201, v201, s0
	v_cvt_pk_bf16_f32 v202, v202, s0
	global_store_short v[198:199], v201, off offset:640
	global_store_short v[198:199], v202, off offset:704
	v_mul_f32_e32 v200, 0x3dd53b94, v158
	v_mul_f32_e32 v94, v94, v200
	v_mul_f32_e32 v78, v78, v200
	s_waitcnt vmcnt(30)
	v_mul_f32_e32 v201, v78, v209
	v_fma_f32 v201, v208, v94, -v201
	v_mul_f32_e32 v202, v94, v209
	v_fmac_f32_e32 v202, v208, v78
	v_cvt_pk_bf16_f32 v201, v201, s0
	v_cvt_pk_bf16_f32 v202, v202, s0
	global_store_short v[198:199], v201, off offset:1024
	global_store_short v[198:199], v202, off offset:1088
	v_mul_f32_e32 v200, 0x3dd53b94, v159
	v_mul_f32_e32 v95, v95, v200
	v_mul_f32_e32 v79, v79, v200
	s_waitcnt vmcnt(30)
	v_mul_f32_e32 v201, v79, v211
	v_fma_f32 v201, v210, v95, -v201
	v_mul_f32_e32 v202, v95, v211
	v_fmac_f32_e32 v202, v210, v79
	v_cvt_pk_bf16_f32 v201, v201, s0
	v_cvt_pk_bf16_f32 v202, v202, s0
	global_store_short v[198:199], v201, off offset:1408
	global_store_short v[198:199], v202, off offset:1472
	v_add_co_u32_e32 v140, vcc, 0x4000, v132
	s_nop 1
	v_addc_co_u32_e32 v141, vcc, 0, v133, vcc
	v_add_co_u32_e32 v142, vcc, 0x5000, v132
	s_nop 1
	v_addc_co_u32_e32 v143, vcc, 0, v133, vcc
	ds_read_b128 v[144:147], v216 offset:49408
	ds_read_b128 v[148:151], v216 offset:49440
	ds_read_b128 v[152:155], v216 offset:49472
	ds_read_b128 v[156:159], v216 offset:49504
	global_load_dword v160, v[140:141], off
	global_load_dword v161, v[140:141], off offset:128
	global_load_dword v162, v[140:141], off offset:256
	global_load_dword v163, v[140:141], off offset:384
	global_load_dword v164, v[140:141], off offset:512
	global_load_dword v165, v[140:141], off offset:640
	global_load_dword v166, v[140:141], off offset:768
	global_load_dword v167, v[140:141], off offset:896
	global_load_dword v168, v[140:141], off offset:2048
	global_load_dword v169, v[140:141], off offset:2176
	global_load_dword v170, v[140:141], off offset:2304
	global_load_dword v171, v[140:141], off offset:2432
	global_load_dword v172, v[140:141], off offset:2560
	global_load_dword v173, v[140:141], off offset:2688
	global_load_dword v174, v[140:141], off offset:2816
	global_load_dword v175, v[140:141], off offset:2944
	global_load_dword v176, v[142:143], off
	global_load_dword v177, v[142:143], off offset:128
	global_load_dword v178, v[142:143], off offset:256
	global_load_dword v179, v[142:143], off offset:384
	global_load_dword v180, v[142:143], off offset:512
	global_load_dword v181, v[142:143], off offset:640
	global_load_dword v182, v[142:143], off offset:768
	global_load_dword v183, v[142:143], off offset:896
	global_load_dword v204, v[142:143], off offset:2048
	global_load_dword v205, v[142:143], off offset:2176
	global_load_dword v206, v[142:143], off offset:2304
	global_load_dword v207, v[142:143], off offset:2432
	global_load_dword v208, v[142:143], off offset:2560
	global_load_dword v209, v[142:143], off offset:2688
	global_load_dword v210, v[142:143], off offset:2816
	global_load_dword v211, v[142:143], off offset:2944
	v_add_co_u32_e32 v192, vcc, 0x6000, v138
	s_nop 1
	v_addc_co_u32_e32 v193, vcc, 0, v139, vcc
	v_add_co_u32_e32 v194, vcc, 0x6c00, v138
	s_nop 1
	v_addc_co_u32_e32 v195, vcc, 0, v139, vcc
	v_add_co_u32_e32 v196, vcc, 0x7800, v138
	s_nop 1
	v_addc_co_u32_e32 v197, vcc, 0, v139, vcc
	v_add_co_u32_e32 v198, vcc, 0x8400, v138
	s_nop 1
	v_addc_co_u32_e32 v199, vcc, 0, v139, vcc
	s_waitcnt lgkmcnt(0)
	v_mul_f32_e32 v200, 0x3dd53b94, v144
	v_mul_f32_e32 v48, v48, v200
	v_mul_f32_e32 v32, v32, v200
	s_waitcnt vmcnt(30)
	v_mul_f32_e32 v201, v32, v161
	v_fma_f32 v201, v160, v48, -v201
	v_mul_f32_e32 v202, v48, v161
	v_fmac_f32_e32 v202, v160, v32
	v_cvt_pk_bf16_f32 v201, v201, s0
	v_cvt_pk_bf16_f32 v202, v202, s0
	global_store_short v[192:193], v201, off offset:256
	global_store_short v[192:193], v202, off offset:320
	v_mul_f32_e32 v200, 0x3dd53b94, v145
	v_mul_f32_e32 v49, v49, v200
	v_mul_f32_e32 v33, v33, v200
	s_waitcnt vmcnt(30)
	v_mul_f32_e32 v201, v33, v163
	v_fma_f32 v201, v162, v49, -v201
	v_mul_f32_e32 v202, v49, v163
	v_fmac_f32_e32 v202, v162, v33
	v_cvt_pk_bf16_f32 v201, v201, s0
	v_cvt_pk_bf16_f32 v202, v202, s0
	global_store_short v[192:193], v201, off offset:640
	global_store_short v[192:193], v202, off offset:704
	v_mul_f32_e32 v200, 0x3dd53b94, v146
	v_mul_f32_e32 v50, v50, v200
	v_mul_f32_e32 v34, v34, v200
	s_waitcnt vmcnt(30)
	v_mul_f32_e32 v201, v34, v165
	v_fma_f32 v201, v164, v50, -v201
	v_mul_f32_e32 v202, v50, v165
	v_fmac_f32_e32 v202, v164, v34
	v_cvt_pk_bf16_f32 v201, v201, s0
	v_cvt_pk_bf16_f32 v202, v202, s0
	global_store_short v[192:193], v201, off offset:1024
	global_store_short v[192:193], v202, off offset:1088
	v_mul_f32_e32 v200, 0x3dd53b94, v147
	v_mul_f32_e32 v51, v51, v200
	v_mul_f32_e32 v35, v35, v200
	s_waitcnt vmcnt(30)
	v_mul_f32_e32 v201, v35, v167
	v_fma_f32 v201, v166, v51, -v201
	v_mul_f32_e32 v202, v51, v167
	v_fmac_f32_e32 v202, v166, v35
	v_cvt_pk_bf16_f32 v201, v201, s0
	v_cvt_pk_bf16_f32 v202, v202, s0
	global_store_short v[192:193], v201, off offset:1408
	global_store_short v[192:193], v202, off offset:1472
	v_mul_f32_e32 v200, 0x3dd53b94, v148
	v_mul_f32_e32 v52, v52, v200
	v_mul_f32_e32 v36, v36, v200
	s_waitcnt vmcnt(30)
	v_mul_f32_e32 v201, v36, v169
	v_fma_f32 v201, v168, v52, -v201
	v_mul_f32_e32 v202, v52, v169
	v_fmac_f32_e32 v202, v168, v36
	v_cvt_pk_bf16_f32 v201, v201, s0
	v_cvt_pk_bf16_f32 v202, v202, s0
	global_store_short v[194:195], v201, off offset:256
	global_store_short v[194:195], v202, off offset:320
	v_mul_f32_e32 v200, 0x3dd53b94, v149
	v_mul_f32_e32 v53, v53, v200
	v_mul_f32_e32 v37, v37, v200
	s_waitcnt vmcnt(30)
	v_mul_f32_e32 v201, v37, v171
	v_fma_f32 v201, v170, v53, -v201
	v_mul_f32_e32 v202, v53, v171
	v_fmac_f32_e32 v202, v170, v37
	v_cvt_pk_bf16_f32 v201, v201, s0
	v_cvt_pk_bf16_f32 v202, v202, s0
	global_store_short v[194:195], v201, off offset:640
	global_store_short v[194:195], v202, off offset:704
	v_mul_f32_e32 v200, 0x3dd53b94, v150
	v_mul_f32_e32 v54, v54, v200
	v_mul_f32_e32 v38, v38, v200
	s_waitcnt vmcnt(30)
	v_mul_f32_e32 v201, v38, v173
	v_fma_f32 v201, v172, v54, -v201
	v_mul_f32_e32 v202, v54, v173
	v_fmac_f32_e32 v202, v172, v38
	v_cvt_pk_bf16_f32 v201, v201, s0
	v_cvt_pk_bf16_f32 v202, v202, s0
	global_store_short v[194:195], v201, off offset:1024
	global_store_short v[194:195], v202, off offset:1088
	v_mul_f32_e32 v200, 0x3dd53b94, v151
	v_mul_f32_e32 v55, v55, v200
	v_mul_f32_e32 v39, v39, v200
	s_waitcnt vmcnt(30)
	v_mul_f32_e32 v201, v39, v175
	v_fma_f32 v201, v174, v55, -v201
	v_mul_f32_e32 v202, v55, v175
	v_fmac_f32_e32 v202, v174, v39
	v_cvt_pk_bf16_f32 v201, v201, s0
	v_cvt_pk_bf16_f32 v202, v202, s0
	global_store_short v[194:195], v201, off offset:1408
	global_store_short v[194:195], v202, off offset:1472
	v_mul_f32_e32 v200, 0x3dd53b94, v152
	v_mul_f32_e32 v56, v56, v200
	v_mul_f32_e32 v40, v40, v200
	s_waitcnt vmcnt(30)
	v_mul_f32_e32 v201, v40, v177
	v_fma_f32 v201, v176, v56, -v201
	v_mul_f32_e32 v202, v56, v177
	v_fmac_f32_e32 v202, v176, v40
	v_cvt_pk_bf16_f32 v201, v201, s0
	v_cvt_pk_bf16_f32 v202, v202, s0
	global_store_short v[196:197], v201, off offset:256
	global_store_short v[196:197], v202, off offset:320
	v_mul_f32_e32 v200, 0x3dd53b94, v153
	v_mul_f32_e32 v57, v57, v200
	v_mul_f32_e32 v41, v41, v200
	s_waitcnt vmcnt(30)
	v_mul_f32_e32 v201, v41, v179
	v_fma_f32 v201, v178, v57, -v201
	v_mul_f32_e32 v202, v57, v179
	v_fmac_f32_e32 v202, v178, v41
	v_cvt_pk_bf16_f32 v201, v201, s0
	v_cvt_pk_bf16_f32 v202, v202, s0
	global_store_short v[196:197], v201, off offset:640
	global_store_short v[196:197], v202, off offset:704
	v_mul_f32_e32 v200, 0x3dd53b94, v154
	v_mul_f32_e32 v58, v58, v200
	v_mul_f32_e32 v42, v42, v200
	s_waitcnt vmcnt(30)
	v_mul_f32_e32 v201, v42, v181
	v_fma_f32 v201, v180, v58, -v201
	v_mul_f32_e32 v202, v58, v181
	v_fmac_f32_e32 v202, v180, v42
	v_cvt_pk_bf16_f32 v201, v201, s0
	v_cvt_pk_bf16_f32 v202, v202, s0
	global_store_short v[196:197], v201, off offset:1024
	global_store_short v[196:197], v202, off offset:1088
	v_mul_f32_e32 v200, 0x3dd53b94, v155
	v_mul_f32_e32 v59, v59, v200
	v_mul_f32_e32 v43, v43, v200
	s_waitcnt vmcnt(30)
	v_mul_f32_e32 v201, v43, v183
	v_fma_f32 v201, v182, v59, -v201
	v_mul_f32_e32 v202, v59, v183
	v_fmac_f32_e32 v202, v182, v43
	v_cvt_pk_bf16_f32 v201, v201, s0
	v_cvt_pk_bf16_f32 v202, v202, s0
	global_store_short v[196:197], v201, off offset:1408
	global_store_short v[196:197], v202, off offset:1472
	v_mul_f32_e32 v200, 0x3dd53b94, v156
	v_mul_f32_e32 v60, v60, v200
	v_mul_f32_e32 v44, v44, v200
	s_waitcnt vmcnt(30)
	v_mul_f32_e32 v201, v44, v205
	v_fma_f32 v201, v204, v60, -v201
	v_mul_f32_e32 v202, v60, v205
	v_fmac_f32_e32 v202, v204, v44
	v_cvt_pk_bf16_f32 v201, v201, s0
	v_cvt_pk_bf16_f32 v202, v202, s0
	global_store_short v[198:199], v201, off offset:256
	global_store_short v[198:199], v202, off offset:320
	v_mul_f32_e32 v200, 0x3dd53b94, v157
	v_mul_f32_e32 v61, v61, v200
	v_mul_f32_e32 v45, v45, v200
	s_waitcnt vmcnt(30)
	v_mul_f32_e32 v201, v45, v207
	v_fma_f32 v201, v206, v61, -v201
	v_mul_f32_e32 v202, v61, v207
	v_fmac_f32_e32 v202, v206, v45
	v_cvt_pk_bf16_f32 v201, v201, s0
	v_cvt_pk_bf16_f32 v202, v202, s0
	global_store_short v[198:199], v201, off offset:640
	global_store_short v[198:199], v202, off offset:704
	v_mul_f32_e32 v200, 0x3dd53b94, v158
	v_mul_f32_e32 v62, v62, v200
	v_mul_f32_e32 v46, v46, v200
	s_waitcnt vmcnt(30)
	v_mul_f32_e32 v201, v46, v209
	v_fma_f32 v201, v208, v62, -v201
	v_mul_f32_e32 v202, v62, v209
	v_fmac_f32_e32 v202, v208, v46
	v_cvt_pk_bf16_f32 v201, v201, s0
	v_cvt_pk_bf16_f32 v202, v202, s0
	global_store_short v[198:199], v201, off offset:1024
	global_store_short v[198:199], v202, off offset:1088
	v_mul_f32_e32 v200, 0x3dd53b94, v159
	v_mul_f32_e32 v63, v63, v200
	v_mul_f32_e32 v47, v47, v200
	s_waitcnt vmcnt(30)
	v_mul_f32_e32 v201, v47, v211
	v_fma_f32 v201, v210, v63, -v201
	v_mul_f32_e32 v202, v63, v211
	v_fmac_f32_e32 v202, v210, v47
	v_cvt_pk_bf16_f32 v201, v201, s0
	v_cvt_pk_bf16_f32 v202, v202, s0
	global_store_short v[198:199], v201, off offset:1408
	global_store_short v[198:199], v202, off offset:1472
	v_add_co_u32_e32 v140, vcc, 0x6000, v132
	s_nop 1
	v_addc_co_u32_e32 v141, vcc, 0, v133, vcc
	v_add_co_u32_e32 v142, vcc, 0x7000, v132
	s_nop 1
	v_addc_co_u32_e32 v143, vcc, 0, v133, vcc
	ds_read_b128 v[144:147], v216 offset:49536
	ds_read_b128 v[148:151], v216 offset:49568
	ds_read_b128 v[152:155], v216 offset:49600
	ds_read_b128 v[156:159], v216 offset:49632
	global_load_dword v160, v[140:141], off
	global_load_dword v161, v[140:141], off offset:128
	global_load_dword v162, v[140:141], off offset:256
	global_load_dword v163, v[140:141], off offset:384
	global_load_dword v164, v[140:141], off offset:512
	global_load_dword v165, v[140:141], off offset:640
	global_load_dword v166, v[140:141], off offset:768
	global_load_dword v167, v[140:141], off offset:896
	global_load_dword v168, v[140:141], off offset:2048
	global_load_dword v169, v[140:141], off offset:2176
	global_load_dword v170, v[140:141], off offset:2304
	global_load_dword v171, v[140:141], off offset:2432
	global_load_dword v172, v[140:141], off offset:2560
	global_load_dword v173, v[140:141], off offset:2688
	global_load_dword v174, v[140:141], off offset:2816
	global_load_dword v175, v[140:141], off offset:2944
	global_load_dword v176, v[142:143], off
	global_load_dword v177, v[142:143], off offset:128
	global_load_dword v178, v[142:143], off offset:256
	global_load_dword v179, v[142:143], off offset:384
	global_load_dword v180, v[142:143], off offset:512
	global_load_dword v181, v[142:143], off offset:640
	global_load_dword v182, v[142:143], off offset:768
	global_load_dword v183, v[142:143], off offset:896
	global_load_dword v204, v[142:143], off offset:2048
	global_load_dword v205, v[142:143], off offset:2176
	global_load_dword v206, v[142:143], off offset:2304
	global_load_dword v207, v[142:143], off offset:2432
	global_load_dword v208, v[142:143], off offset:2560
	global_load_dword v209, v[142:143], off offset:2688
	global_load_dword v210, v[142:143], off offset:2816
	global_load_dword v211, v[142:143], off offset:2944
	v_add_co_u32_e32 v192, vcc, 0x9000, v138
	s_nop 1
	v_addc_co_u32_e32 v193, vcc, 0, v139, vcc
	v_add_co_u32_e32 v194, vcc, 0x9c00, v138
	s_nop 1
	v_addc_co_u32_e32 v195, vcc, 0, v139, vcc
	v_add_co_u32_e32 v196, vcc, 0xa800, v138
	s_nop 1
	v_addc_co_u32_e32 v197, vcc, 0, v139, vcc
	v_add_co_u32_e32 v198, vcc, 0xb400, v138
	s_nop 1
	v_addc_co_u32_e32 v199, vcc, 0, v139, vcc
	s_waitcnt lgkmcnt(0)
	v_mul_f32_e32 v200, 0x3dd53b94, v144
	v_mul_f32_e32 v16, v16, v200
	v_mul_f32_e32 v0, v0, v200
	s_waitcnt vmcnt(30)
	v_mul_f32_e32 v201, v0, v161
	v_fma_f32 v201, v160, v16, -v201
	v_mul_f32_e32 v202, v16, v161
	v_fmac_f32_e32 v202, v160, v0
	v_cvt_pk_bf16_f32 v201, v201, s0
	v_cvt_pk_bf16_f32 v202, v202, s0
	global_store_short v[192:193], v201, off offset:256
	global_store_short v[192:193], v202, off offset:320
	v_mul_f32_e32 v200, 0x3dd53b94, v145
	v_mul_f32_e32 v17, v17, v200
	v_mul_f32_e32 v1, v1, v200
	s_waitcnt vmcnt(30)
	v_mul_f32_e32 v201, v1, v163
	v_fma_f32 v201, v162, v17, -v201
	v_mul_f32_e32 v202, v17, v163
	v_fmac_f32_e32 v202, v162, v1
	v_cvt_pk_bf16_f32 v201, v201, s0
	v_cvt_pk_bf16_f32 v202, v202, s0
	global_store_short v[192:193], v201, off offset:640
	global_store_short v[192:193], v202, off offset:704
	v_mul_f32_e32 v200, 0x3dd53b94, v146
	v_mul_f32_e32 v18, v18, v200
	v_mul_f32_e32 v2, v2, v200
	s_waitcnt vmcnt(30)
	v_mul_f32_e32 v201, v2, v165
	v_fma_f32 v201, v164, v18, -v201
	v_mul_f32_e32 v202, v18, v165
	v_fmac_f32_e32 v202, v164, v2
	v_cvt_pk_bf16_f32 v201, v201, s0
	v_cvt_pk_bf16_f32 v202, v202, s0
	global_store_short v[192:193], v201, off offset:1024
	global_store_short v[192:193], v202, off offset:1088
	v_mul_f32_e32 v200, 0x3dd53b94, v147
	v_mul_f32_e32 v19, v19, v200
	v_mul_f32_e32 v3, v3, v200
	s_waitcnt vmcnt(30)
	v_mul_f32_e32 v201, v3, v167
	v_fma_f32 v201, v166, v19, -v201
	v_mul_f32_e32 v202, v19, v167
	v_fmac_f32_e32 v202, v166, v3
	v_cvt_pk_bf16_f32 v201, v201, s0
	v_cvt_pk_bf16_f32 v202, v202, s0
	global_store_short v[192:193], v201, off offset:1408
	global_store_short v[192:193], v202, off offset:1472
	v_mul_f32_e32 v200, 0x3dd53b94, v148
	v_mul_f32_e32 v20, v20, v200
	v_mul_f32_e32 v4, v4, v200
	s_waitcnt vmcnt(30)
	v_mul_f32_e32 v201, v4, v169
	v_fma_f32 v201, v168, v20, -v201
	v_mul_f32_e32 v202, v20, v169
	v_fmac_f32_e32 v202, v168, v4
	v_cvt_pk_bf16_f32 v201, v201, s0
	v_cvt_pk_bf16_f32 v202, v202, s0
	global_store_short v[194:195], v201, off offset:256
	global_store_short v[194:195], v202, off offset:320
	v_mul_f32_e32 v200, 0x3dd53b94, v149
	v_mul_f32_e32 v21, v21, v200
	v_mul_f32_e32 v5, v5, v200
	s_waitcnt vmcnt(30)
	v_mul_f32_e32 v201, v5, v171
	v_fma_f32 v201, v170, v21, -v201
	v_mul_f32_e32 v202, v21, v171
	v_fmac_f32_e32 v202, v170, v5
	v_cvt_pk_bf16_f32 v201, v201, s0
	v_cvt_pk_bf16_f32 v202, v202, s0
	global_store_short v[194:195], v201, off offset:640
	global_store_short v[194:195], v202, off offset:704
	v_mul_f32_e32 v200, 0x3dd53b94, v150
	v_mul_f32_e32 v22, v22, v200
	v_mul_f32_e32 v6, v6, v200
	s_waitcnt vmcnt(30)
	v_mul_f32_e32 v201, v6, v173
	v_fma_f32 v201, v172, v22, -v201
	v_mul_f32_e32 v202, v22, v173
	v_fmac_f32_e32 v202, v172, v6
	v_cvt_pk_bf16_f32 v201, v201, s0
	v_cvt_pk_bf16_f32 v202, v202, s0
	global_store_short v[194:195], v201, off offset:1024
	global_store_short v[194:195], v202, off offset:1088
	v_mul_f32_e32 v200, 0x3dd53b94, v151
	v_mul_f32_e32 v23, v23, v200
	v_mul_f32_e32 v7, v7, v200
	s_waitcnt vmcnt(30)
	v_mul_f32_e32 v201, v7, v175
	v_fma_f32 v201, v174, v23, -v201
	v_mul_f32_e32 v202, v23, v175
	v_fmac_f32_e32 v202, v174, v7
	v_cvt_pk_bf16_f32 v201, v201, s0
	v_cvt_pk_bf16_f32 v202, v202, s0
	global_store_short v[194:195], v201, off offset:1408
	global_store_short v[194:195], v202, off offset:1472
	v_mul_f32_e32 v200, 0x3dd53b94, v152
	v_mul_f32_e32 v24, v24, v200
	v_mul_f32_e32 v8, v8, v200
	s_waitcnt vmcnt(30)
	v_mul_f32_e32 v201, v8, v177
	v_fma_f32 v201, v176, v24, -v201
	v_mul_f32_e32 v202, v24, v177
	v_fmac_f32_e32 v202, v176, v8
	v_cvt_pk_bf16_f32 v201, v201, s0
	v_cvt_pk_bf16_f32 v202, v202, s0
	global_store_short v[196:197], v201, off offset:256
	global_store_short v[196:197], v202, off offset:320
	v_mul_f32_e32 v200, 0x3dd53b94, v153
	v_mul_f32_e32 v25, v25, v200
	v_mul_f32_e32 v9, v9, v200
	s_waitcnt vmcnt(30)
	v_mul_f32_e32 v201, v9, v179
	v_fma_f32 v201, v178, v25, -v201
	v_mul_f32_e32 v202, v25, v179
	v_fmac_f32_e32 v202, v178, v9
	v_cvt_pk_bf16_f32 v201, v201, s0
	v_cvt_pk_bf16_f32 v202, v202, s0
	global_store_short v[196:197], v201, off offset:640
	global_store_short v[196:197], v202, off offset:704
	v_mul_f32_e32 v200, 0x3dd53b94, v154
	v_mul_f32_e32 v26, v26, v200
	v_mul_f32_e32 v10, v10, v200
	s_waitcnt vmcnt(30)
	v_mul_f32_e32 v201, v10, v181
	v_fma_f32 v201, v180, v26, -v201
	v_mul_f32_e32 v202, v26, v181
	v_fmac_f32_e32 v202, v180, v10
	v_cvt_pk_bf16_f32 v201, v201, s0
	v_cvt_pk_bf16_f32 v202, v202, s0
	global_store_short v[196:197], v201, off offset:1024
	global_store_short v[196:197], v202, off offset:1088
	v_mul_f32_e32 v200, 0x3dd53b94, v155
	v_mul_f32_e32 v27, v27, v200
	v_mul_f32_e32 v11, v11, v200
	s_waitcnt vmcnt(30)
	v_mul_f32_e32 v201, v11, v183
	v_fma_f32 v201, v182, v27, -v201
	v_mul_f32_e32 v202, v27, v183
	v_fmac_f32_e32 v202, v182, v11
	v_cvt_pk_bf16_f32 v201, v201, s0
	v_cvt_pk_bf16_f32 v202, v202, s0
	global_store_short v[196:197], v201, off offset:1408
	global_store_short v[196:197], v202, off offset:1472
	v_mul_f32_e32 v200, 0x3dd53b94, v156
	v_mul_f32_e32 v28, v28, v200
	v_mul_f32_e32 v12, v12, v200
	s_waitcnt vmcnt(30)
	v_mul_f32_e32 v201, v12, v205
	v_fma_f32 v201, v204, v28, -v201
	v_mul_f32_e32 v202, v28, v205
	v_fmac_f32_e32 v202, v204, v12
	v_cvt_pk_bf16_f32 v201, v201, s0
	v_cvt_pk_bf16_f32 v202, v202, s0
	global_store_short v[198:199], v201, off offset:256
	global_store_short v[198:199], v202, off offset:320
	v_mul_f32_e32 v200, 0x3dd53b94, v157
	v_mul_f32_e32 v29, v29, v200
	v_mul_f32_e32 v13, v13, v200
	s_waitcnt vmcnt(30)
	v_mul_f32_e32 v201, v13, v207
	v_fma_f32 v201, v206, v29, -v201
	v_mul_f32_e32 v202, v29, v207
	v_fmac_f32_e32 v202, v206, v13
	v_cvt_pk_bf16_f32 v201, v201, s0
	v_cvt_pk_bf16_f32 v202, v202, s0
	global_store_short v[198:199], v201, off offset:640
	global_store_short v[198:199], v202, off offset:704
	v_mul_f32_e32 v200, 0x3dd53b94, v158
	v_mul_f32_e32 v30, v30, v200
	v_mul_f32_e32 v14, v14, v200
	s_waitcnt vmcnt(30)
	v_mul_f32_e32 v201, v14, v209
	v_fma_f32 v201, v208, v30, -v201
	v_mul_f32_e32 v202, v30, v209
	v_fmac_f32_e32 v202, v208, v14
	v_cvt_pk_bf16_f32 v201, v201, s0
	v_cvt_pk_bf16_f32 v202, v202, s0
	global_store_short v[198:199], v201, off offset:1024
	global_store_short v[198:199], v202, off offset:1088
	v_mul_f32_e32 v200, 0x3dd53b94, v159
	v_mul_f32_e32 v31, v31, v200
	v_mul_f32_e32 v15, v15, v200
	s_waitcnt vmcnt(30)
	v_mul_f32_e32 v201, v15, v211
	v_fma_f32 v201, v210, v31, -v201
	v_mul_f32_e32 v202, v31, v211
	v_fmac_f32_e32 v202, v210, v15
	v_cvt_pk_bf16_f32 v201, v201, s0
	v_cvt_pk_bf16_f32 v202, v202, s0
	global_store_short v[198:199], v201, off offset:1408
	global_store_short v[198:199], v202, off offset:1472
	s_branch .LBB0_63

.LBB0_94:
	s_cmp_eq_u32 s100, 1
	s_cbranch_scc1 .Lp9_after_gate
	s_add_i32 s5, s5, s64
	s_add_i32 s4, s4, s51
	s_cmpk_eq_i32 s64, 0x200
	s_cbranch_scc1 .LBB0_127
	s_cmpk_gt_i32 s5, 0x31f
	s_cbranch_scc1 .LBB0_127

.LBB0_120:
	s_or_b64 exec, exec, s[24:25]
	s_and_saveexec_b64 s[10:11], s[2:3]
	s_cbranch_execz .LBB0_122
	v_and_b32_e32 v130, 31, v189
	v_and_b32_e32 v129, 0xffffff80, v189
	v_lshrrev_b32_e32 v128, 3, v189
	v_and_b32_e32 v128, 4, v128
	v_add3_u32 v131, v129, s7, v128
	v_lshlrev_b32_e32 v186, 1, v130
	v_lshlrev_b32_e32 v132, 8, v131
	v_lshl_add_u32 v132, v130, 2, v132
	v_mov_b32_e32 v133, 0
	v_lshl_add_u64 v[132:133], s[22:23], 0, v[132:133]
	v_lshlrev_b32_e32 v134, 7, v131
	v_add_u32_e32 v134, v134, v186
	v_mov_b32_e32 v135, 0
	v_lshl_add_u64 v[134:135], s[20:21], 0, v[134:135]
	v_add_co_u32_e32 v140, vcc, 0x0, v132
	s_nop 1
	v_addc_co_u32_e32 v141, vcc, 0, v133, vcc
	v_add_co_u32_e32 v142, vcc, 0x1000, v132
	s_nop 1
	v_addc_co_u32_e32 v143, vcc, 0, v133, vcc
	global_load_dword v160, v[140:141], off
	global_load_dword v161, v[140:141], off offset:128
	global_load_dword v162, v[140:141], off offset:256
	global_load_dword v163, v[140:141], off offset:384
	global_load_dword v164, v[140:141], off offset:512
	global_load_dword v165, v[140:141], off offset:640
	global_load_dword v166, v[140:141], off offset:768
	global_load_dword v167, v[140:141], off offset:896
	global_load_dword v168, v[140:141], off offset:2048
	global_load_dword v169, v[140:141], off offset:2176
	global_load_dword v170, v[140:141], off offset:2304
	global_load_dword v171, v[140:141], off offset:2432
	global_load_dword v172, v[140:141], off offset:2560
	global_load_dword v173, v[140:141], off offset:2688
	global_load_dword v174, v[140:141], off offset:2816
	global_load_dword v175, v[140:141], off offset:2944
	global_load_dword v176, v[142:143], off
	global_load_dword v177, v[142:143], off offset:128
	global_load_dword v178, v[142:143], off offset:256
	global_load_dword v179, v[142:143], off offset:384
	global_load_dword v180, v[142:143], off offset:512
	global_load_dword v181, v[142:143], off offset:640
	global_load_dword v182, v[142:143], off offset:768
	global_load_dword v183, v[142:143], off offset:896
	global_load_dword v204, v[142:143], off offset:2048
	global_load_dword v205, v[142:143], off offset:2176
	global_load_dword v206, v[142:143], off offset:2304
	global_load_dword v207, v[142:143], off offset:2432
	global_load_dword v208, v[142:143], off offset:2560
	global_load_dword v209, v[142:143], off offset:2688
	global_load_dword v210, v[142:143], off offset:2816
	global_load_dword v211, v[142:143], off offset:2944
	v_mov_b64_e32 v[192:193], v[134:135]
	s_waitcnt vmcnt(30)
	v_mul_f32_e32 v201, v96, v161
	v_fma_f32 v201, v112, v160, -v201
	v_mul_f32_e32 v202, v112, v161
	v_fmac_f32_e32 v202, v96, v160
	v_cvt_pk_bf16_f32 v201, v201, s0
	v_cvt_pk_bf16_f32 v202, v202, s0
	global_store_short v[192:193], v201, off
	global_store_short v[192:193], v202, off offset:64
	s_waitcnt vmcnt(30)
	v_mul_f32_e32 v201, v97, v163
	v_fma_f32 v201, v113, v162, -v201
	v_mul_f32_e32 v202, v113, v163
	v_fmac_f32_e32 v202, v97, v162
	v_cvt_pk_bf16_f32 v201, v201, s0
	v_cvt_pk_bf16_f32 v202, v202, s0
	global_store_short v[192:193], v201, off offset:128
	global_store_short v[192:193], v202, off offset:192
	s_waitcnt vmcnt(30)
	v_mul_f32_e32 v201, v98, v165
	v_fma_f32 v201, v114, v164, -v201
	v_mul_f32_e32 v202, v114, v165
	v_fmac_f32_e32 v202, v98, v164
	v_cvt_pk_bf16_f32 v201, v201, s0
	v_cvt_pk_bf16_f32 v202, v202, s0
	global_store_short v[192:193], v201, off offset:256
	global_store_short v[192:193], v202, off offset:320
	s_waitcnt vmcnt(30)
	v_mul_f32_e32 v201, v99, v167
	v_fma_f32 v201, v115, v166, -v201
	v_mul_f32_e32 v202, v115, v167
	v_fmac_f32_e32 v202, v99, v166
	v_cvt_pk_bf16_f32 v201, v201, s0
	v_cvt_pk_bf16_f32 v202, v202, s0
	global_store_short v[192:193], v201, off offset:384
	global_store_short v[192:193], v202, off offset:448
	s_waitcnt vmcnt(30)
	v_mul_f32_e32 v201, v100, v169
	v_fma_f32 v201, v116, v168, -v201
	v_mul_f32_e32 v202, v116, v169
	v_fmac_f32_e32 v202, v100, v168
	v_cvt_pk_bf16_f32 v201, v201, s0
	v_cvt_pk_bf16_f32 v202, v202, s0
	global_store_short v[192:193], v201, off offset:1024
	global_store_short v[192:193], v202, off offset:1088
	s_waitcnt vmcnt(30)
	v_mul_f32_e32 v201, v101, v171
	v_fma_f32 v201, v117, v170, -v201
	v_mul_f32_e32 v202, v117, v171
	v_fmac_f32_e32 v202, v101, v170
	v_cvt_pk_bf16_f32 v201, v201, s0
	v_cvt_pk_bf16_f32 v202, v202, s0
	global_store_short v[192:193], v201, off offset:1152
	global_store_short v[192:193], v202, off offset:1216
	s_waitcnt vmcnt(30)
	v_mul_f32_e32 v201, v102, v173
	v_fma_f32 v201, v118, v172, -v201
	v_mul_f32_e32 v202, v118, v173
	v_fmac_f32_e32 v202, v102, v172
	v_cvt_pk_bf16_f32 v201, v201, s0
	v_cvt_pk_bf16_f32 v202, v202, s0
	global_store_short v[192:193], v201, off offset:1280
	global_store_short v[192:193], v202, off offset:1344
	s_waitcnt vmcnt(30)
	v_mul_f32_e32 v201, v103, v175
	v_fma_f32 v201, v119, v174, -v201
	v_mul_f32_e32 v202, v119, v175
	v_fmac_f32_e32 v202, v103, v174
	v_cvt_pk_bf16_f32 v201, v201, s0
	v_cvt_pk_bf16_f32 v202, v202, s0
	global_store_short v[192:193], v201, off offset:1408
	global_store_short v[192:193], v202, off offset:1472
	s_waitcnt vmcnt(30)
	v_mul_f32_e32 v201, v104, v177
	v_fma_f32 v201, v120, v176, -v201
	v_mul_f32_e32 v202, v120, v177
	v_fmac_f32_e32 v202, v104, v176
	v_cvt_pk_bf16_f32 v201, v201, s0
	v_cvt_pk_bf16_f32 v202, v202, s0
	global_store_short v[192:193], v201, off offset:2048
	global_store_short v[192:193], v202, off offset:2112
	s_waitcnt vmcnt(30)
	v_mul_f32_e32 v201, v105, v179
	v_fma_f32 v201, v121, v178, -v201
	v_mul_f32_e32 v202, v121, v179
	v_fmac_f32_e32 v202, v105, v178
	v_cvt_pk_bf16_f32 v201, v201, s0
	v_cvt_pk_bf16_f32 v202, v202, s0
	global_store_short v[192:193], v201, off offset:2176
	global_store_short v[192:193], v202, off offset:2240
	s_waitcnt vmcnt(30)
	v_mul_f32_e32 v201, v106, v181
	v_fma_f32 v201, v122, v180, -v201
	v_mul_f32_e32 v202, v122, v181
	v_fmac_f32_e32 v202, v106, v180
	v_cvt_pk_bf16_f32 v201, v201, s0
	v_cvt_pk_bf16_f32 v202, v202, s0
	global_store_short v[192:193], v201, off offset:2304
	global_store_short v[192:193], v202, off offset:2368
	s_waitcnt vmcnt(30)
	v_mul_f32_e32 v201, v107, v183
	v_fma_f32 v201, v123, v182, -v201
	v_mul_f32_e32 v202, v123, v183
	v_fmac_f32_e32 v202, v107, v182
	v_cvt_pk_bf16_f32 v201, v201, s0
	v_cvt_pk_bf16_f32 v202, v202, s0
	global_store_short v[192:193], v201, off offset:2432
	global_store_short v[192:193], v202, off offset:2496
	s_waitcnt vmcnt(30)
	v_mul_f32_e32 v201, v108, v205
	v_fma_f32 v201, v124, v204, -v201
	v_mul_f32_e32 v202, v124, v205
	v_fmac_f32_e32 v202, v108, v204
	v_cvt_pk_bf16_f32 v201, v201, s0
	v_cvt_pk_bf16_f32 v202, v202, s0
	global_store_short v[192:193], v201, off offset:3072
	global_store_short v[192:193], v202, off offset:3136
	s_waitcnt vmcnt(30)
	v_mul_f32_e32 v201, v109, v207
	v_fma_f32 v201, v125, v206, -v201
	v_mul_f32_e32 v202, v125, v207
	v_fmac_f32_e32 v202, v109, v206
	v_cvt_pk_bf16_f32 v201, v201, s0
	v_cvt_pk_bf16_f32 v202, v202, s0
	global_store_short v[192:193], v201, off offset:3200
	global_store_short v[192:193], v202, off offset:3264
	s_waitcnt vmcnt(30)
	v_mul_f32_e32 v201, v110, v209
	v_fma_f32 v201, v126, v208, -v201
	v_mul_f32_e32 v202, v126, v209
	v_fmac_f32_e32 v202, v110, v208
	v_cvt_pk_bf16_f32 v201, v201, s0
	v_cvt_pk_bf16_f32 v202, v202, s0
	global_store_short v[192:193], v201, off offset:3328
	global_store_short v[192:193], v202, off offset:3392
	s_waitcnt vmcnt(30)
	v_mul_f32_e32 v201, v111, v211
	v_fma_f32 v201, v127, v210, -v201
	v_mul_f32_e32 v202, v127, v211
	v_fmac_f32_e32 v202, v111, v210
	v_cvt_pk_bf16_f32 v201, v201, s0
	v_cvt_pk_bf16_f32 v202, v202, s0
	global_store_short v[192:193], v201, off offset:3456
	global_store_short v[192:193], v202, off offset:3520
	v_add_co_u32_e32 v140, vcc, 0x2000, v132
	s_nop 1
	v_addc_co_u32_e32 v141, vcc, 0, v133, vcc
	v_add_co_u32_e32 v142, vcc, 0x3000, v132
	s_nop 1
	v_addc_co_u32_e32 v143, vcc, 0, v133, vcc
	global_load_dword v160, v[140:141], off
	global_load_dword v161, v[140:141], off offset:128
	global_load_dword v162, v[140:141], off offset:256
	global_load_dword v163, v[140:141], off offset:384
	global_load_dword v164, v[140:141], off offset:512
	global_load_dword v165, v[140:141], off offset:640
	global_load_dword v166, v[140:141], off offset:768
	global_load_dword v167, v[140:141], off offset:896
	global_load_dword v168, v[140:141], off offset:2048
	global_load_dword v169, v[140:141], off offset:2176
	global_load_dword v170, v[140:141], off offset:2304
	global_load_dword v171, v[140:141], off offset:2432
	global_load_dword v172, v[140:141], off offset:2560
	global_load_dword v173, v[140:141], off offset:2688
	global_load_dword v174, v[140:141], off offset:2816
	global_load_dword v175, v[140:141], off offset:2944
	global_load_dword v176, v[142:143], off
	global_load_dword v177, v[142:143], off offset:128
	global_load_dword v178, v[142:143], off offset:256
	global_load_dword v179, v[142:143], off offset:384
	global_load_dword v180, v[142:143], off offset:512
	global_load_dword v181, v[142:143], off offset:640
	global_load_dword v182, v[142:143], off offset:768
	global_load_dword v183, v[142:143], off offset:896
	global_load_dword v204, v[142:143], off offset:2048
	global_load_dword v205, v[142:143], off offset:2176
	global_load_dword v206, v[142:143], off offset:2304
	global_load_dword v207, v[142:143], off offset:2432
	global_load_dword v208, v[142:143], off offset:2560
	global_load_dword v209, v[142:143], off offset:2688
	global_load_dword v210, v[142:143], off offset:2816
	global_load_dword v211, v[142:143], off offset:2944
	v_add_co_u32_e32 v192, vcc, 0x1000, v134
	s_nop 1
	v_addc_co_u32_e32 v193, vcc, 0, v135, vcc
	s_waitcnt vmcnt(30)
	v_mul_f32_e32 v201, v64, v161
	v_fma_f32 v201, v80, v160, -v201
	v_mul_f32_e32 v202, v80, v161
	v_fmac_f32_e32 v202, v64, v160
	v_cvt_pk_bf16_f32 v201, v201, s0
	v_cvt_pk_bf16_f32 v202, v202, s0
	global_store_short v[192:193], v201, off
	global_store_short v[192:193], v202, off offset:64
	s_waitcnt vmcnt(30)
	v_mul_f32_e32 v201, v65, v163
	v_fma_f32 v201, v81, v162, -v201
	v_mul_f32_e32 v202, v81, v163
	v_fmac_f32_e32 v202, v65, v162
	v_cvt_pk_bf16_f32 v201, v201, s0
	v_cvt_pk_bf16_f32 v202, v202, s0
	global_store_short v[192:193], v201, off offset:128
	global_store_short v[192:193], v202, off offset:192
	s_waitcnt vmcnt(30)
	v_mul_f32_e32 v201, v66, v165
	v_fma_f32 v201, v82, v164, -v201
	v_mul_f32_e32 v202, v82, v165
	v_fmac_f32_e32 v202, v66, v164
	v_cvt_pk_bf16_f32 v201, v201, s0
	v_cvt_pk_bf16_f32 v202, v202, s0
	global_store_short v[192:193], v201, off offset:256
	global_store_short v[192:193], v202, off offset:320
	s_waitcnt vmcnt(30)
	v_mul_f32_e32 v201, v67, v167
	v_fma_f32 v201, v83, v166, -v201
	v_mul_f32_e32 v202, v83, v167
	v_fmac_f32_e32 v202, v67, v166
	v_cvt_pk_bf16_f32 v201, v201, s0
	v_cvt_pk_bf16_f32 v202, v202, s0
	global_store_short v[192:193], v201, off offset:384
	global_store_short v[192:193], v202, off offset:448
	s_waitcnt vmcnt(30)
	v_mul_f32_e32 v201, v68, v169
	v_fma_f32 v201, v84, v168, -v201
	v_mul_f32_e32 v202, v84, v169
	v_fmac_f32_e32 v202, v68, v168
	v_cvt_pk_bf16_f32 v201, v201, s0
	v_cvt_pk_bf16_f32 v202, v202, s0
	global_store_short v[192:193], v201, off offset:1024
	global_store_short v[192:193], v202, off offset:1088
	s_waitcnt vmcnt(30)
	v_mul_f32_e32 v201, v69, v171
	v_fma_f32 v201, v85, v170, -v201
	v_mul_f32_e32 v202, v85, v171
	v_fmac_f32_e32 v202, v69, v170
	v_cvt_pk_bf16_f32 v201, v201, s0
	v_cvt_pk_bf16_f32 v202, v202, s0
	global_store_short v[192:193], v201, off offset:1152
	global_store_short v[192:193], v202, off offset:1216
	s_waitcnt vmcnt(30)
	v_mul_f32_e32 v201, v70, v173
	v_fma_f32 v201, v86, v172, -v201
	v_mul_f32_e32 v202, v86, v173
	v_fmac_f32_e32 v202, v70, v172
	v_cvt_pk_bf16_f32 v201, v201, s0
	v_cvt_pk_bf16_f32 v202, v202, s0
	global_store_short v[192:193], v201, off offset:1280
	global_store_short v[192:193], v202, off offset:1344
	s_waitcnt vmcnt(30)
	v_mul_f32_e32 v201, v71, v175
	v_fma_f32 v201, v87, v174, -v201
	v_mul_f32_e32 v202, v87, v175
	v_fmac_f32_e32 v202, v71, v174
	v_cvt_pk_bf16_f32 v201, v201, s0
	v_cvt_pk_bf16_f32 v202, v202, s0
	global_store_short v[192:193], v201, off offset:1408
	global_store_short v[192:193], v202, off offset:1472
	s_waitcnt vmcnt(30)
	v_mul_f32_e32 v201, v72, v177
	v_fma_f32 v201, v88, v176, -v201
	v_mul_f32_e32 v202, v88, v177
	v_fmac_f32_e32 v202, v72, v176
	v_cvt_pk_bf16_f32 v201, v201, s0
	v_cvt_pk_bf16_f32 v202, v202, s0
	global_store_short v[192:193], v201, off offset:2048
	global_store_short v[192:193], v202, off offset:2112
	s_waitcnt vmcnt(30)
	v_mul_f32_e32 v201, v73, v179
	v_fma_f32 v201, v89, v178, -v201
	v_mul_f32_e32 v202, v89, v179
	v_fmac_f32_e32 v202, v73, v178
	v_cvt_pk_bf16_f32 v201, v201, s0
	v_cvt_pk_bf16_f32 v202, v202, s0
	global_store_short v[192:193], v201, off offset:2176
	global_store_short v[192:193], v202, off offset:2240
	s_waitcnt vmcnt(30)
	v_mul_f32_e32 v201, v74, v181
	v_fma_f32 v201, v90, v180, -v201
	v_mul_f32_e32 v202, v90, v181
	v_fmac_f32_e32 v202, v74, v180
	v_cvt_pk_bf16_f32 v201, v201, s0
	v_cvt_pk_bf16_f32 v202, v202, s0
	global_store_short v[192:193], v201, off offset:2304
	global_store_short v[192:193], v202, off offset:2368
	s_waitcnt vmcnt(30)
	v_mul_f32_e32 v201, v75, v183
	v_fma_f32 v201, v91, v182, -v201
	v_mul_f32_e32 v202, v91, v183
	v_fmac_f32_e32 v202, v75, v182
	v_cvt_pk_bf16_f32 v201, v201, s0
	v_cvt_pk_bf16_f32 v202, v202, s0
	global_store_short v[192:193], v201, off offset:2432
	global_store_short v[192:193], v202, off offset:2496
	s_waitcnt vmcnt(30)
	v_mul_f32_e32 v201, v76, v205
	v_fma_f32 v201, v92, v204, -v201
	v_mul_f32_e32 v202, v92, v205
	v_fmac_f32_e32 v202, v76, v204
	v_cvt_pk_bf16_f32 v201, v201, s0
	v_cvt_pk_bf16_f32 v202, v202, s0
	global_store_short v[192:193], v201, off offset:3072
	global_store_short v[192:193], v202, off offset:3136
	s_waitcnt vmcnt(30)
	v_mul_f32_e32 v201, v77, v207
	v_fma_f32 v201, v93, v206, -v201
	v_mul_f32_e32 v202, v93, v207
	v_fmac_f32_e32 v202, v77, v206
	v_cvt_pk_bf16_f32 v201, v201, s0
	v_cvt_pk_bf16_f32 v202, v202, s0
	global_store_short v[192:193], v201, off offset:3200
	global_store_short v[192:193], v202, off offset:3264
	s_waitcnt vmcnt(30)
	v_mul_f32_e32 v201, v78, v209
	v_fma_f32 v201, v94, v208, -v201
	v_mul_f32_e32 v202, v94, v209
	v_fmac_f32_e32 v202, v78, v208
	v_cvt_pk_bf16_f32 v201, v201, s0
	v_cvt_pk_bf16_f32 v202, v202, s0
	global_store_short v[192:193], v201, off offset:3328
	global_store_short v[192:193], v202, off offset:3392
	s_waitcnt vmcnt(30)
	v_mul_f32_e32 v201, v79, v211
	v_fma_f32 v201, v95, v210, -v201
	v_mul_f32_e32 v202, v95, v211
	v_fmac_f32_e32 v202, v79, v210
	v_cvt_pk_bf16_f32 v201, v201, s0
	v_cvt_pk_bf16_f32 v202, v202, s0
	global_store_short v[192:193], v201, off offset:3456
	global_store_short v[192:193], v202, off offset:3520
	v_add_co_u32_e32 v140, vcc, 0x4000, v132
	s_nop 1
	v_addc_co_u32_e32 v141, vcc, 0, v133, vcc
	v_add_co_u32_e32 v142, vcc, 0x5000, v132
	s_nop 1
	v_addc_co_u32_e32 v143, vcc, 0, v133, vcc
	global_load_dword v160, v[140:141], off
	global_load_dword v161, v[140:141], off offset:128
	global_load_dword v162, v[140:141], off offset:256
	global_load_dword v163, v[140:141], off offset:384
	global_load_dword v164, v[140:141], off offset:512
	global_load_dword v165, v[140:141], off offset:640
	global_load_dword v166, v[140:141], off offset:768
	global_load_dword v167, v[140:141], off offset:896
	global_load_dword v168, v[140:141], off offset:2048
	global_load_dword v169, v[140:141], off offset:2176
	global_load_dword v170, v[140:141], off offset:2304
	global_load_dword v171, v[140:141], off offset:2432
	global_load_dword v172, v[140:141], off offset:2560
	global_load_dword v173, v[140:141], off offset:2688
	global_load_dword v174, v[140:141], off offset:2816
	global_load_dword v175, v[140:141], off offset:2944
	global_load_dword v176, v[142:143], off
	global_load_dword v177, v[142:143], off offset:128
	global_load_dword v178, v[142:143], off offset:256
	global_load_dword v179, v[142:143], off offset:384
	global_load_dword v180, v[142:143], off offset:512
	global_load_dword v181, v[142:143], off offset:640
	global_load_dword v182, v[142:143], off offset:768
	global_load_dword v183, v[142:143], off offset:896
	global_load_dword v204, v[142:143], off offset:2048
	global_load_dword v205, v[142:143], off offset:2176
	global_load_dword v206, v[142:143], off offset:2304
	global_load_dword v207, v[142:143], off offset:2432
	global_load_dword v208, v[142:143], off offset:2560
	global_load_dword v209, v[142:143], off offset:2688
	global_load_dword v210, v[142:143], off offset:2816
	global_load_dword v211, v[142:143], off offset:2944
	v_add_co_u32_e32 v192, vcc, 0x2000, v134
	s_nop 1
	v_addc_co_u32_e32 v193, vcc, 0, v135, vcc
	s_waitcnt vmcnt(30)
	v_mul_f32_e32 v201, v32, v161
	v_fma_f32 v201, v48, v160, -v201
	v_mul_f32_e32 v202, v48, v161
	v_fmac_f32_e32 v202, v32, v160
	v_cvt_pk_bf16_f32 v201, v201, s0
	v_cvt_pk_bf16_f32 v202, v202, s0
	global_store_short v[192:193], v201, off
	global_store_short v[192:193], v202, off offset:64
	s_waitcnt vmcnt(30)
	v_mul_f32_e32 v201, v33, v163
	v_fma_f32 v201, v49, v162, -v201
	v_mul_f32_e32 v202, v49, v163
	v_fmac_f32_e32 v202, v33, v162
	v_cvt_pk_bf16_f32 v201, v201, s0
	v_cvt_pk_bf16_f32 v202, v202, s0
	global_store_short v[192:193], v201, off offset:128
	global_store_short v[192:193], v202, off offset:192
	s_waitcnt vmcnt(30)
	v_mul_f32_e32 v201, v34, v165
	v_fma_f32 v201, v50, v164, -v201
	v_mul_f32_e32 v202, v50, v165
	v_fmac_f32_e32 v202, v34, v164
	v_cvt_pk_bf16_f32 v201, v201, s0
	v_cvt_pk_bf16_f32 v202, v202, s0
	global_store_short v[192:193], v201, off offset:256
	global_store_short v[192:193], v202, off offset:320
	s_waitcnt vmcnt(30)
	v_mul_f32_e32 v201, v35, v167
	v_fma_f32 v201, v51, v166, -v201
	v_mul_f32_e32 v202, v51, v167
	v_fmac_f32_e32 v202, v35, v166
	v_cvt_pk_bf16_f32 v201, v201, s0
	v_cvt_pk_bf16_f32 v202, v202, s0
	global_store_short v[192:193], v201, off offset:384
	global_store_short v[192:193], v202, off offset:448
	s_waitcnt vmcnt(30)
	v_mul_f32_e32 v201, v36, v169
	v_fma_f32 v201, v52, v168, -v201
	v_mul_f32_e32 v202, v52, v169
	v_fmac_f32_e32 v202, v36, v168
	v_cvt_pk_bf16_f32 v201, v201, s0
	v_cvt_pk_bf16_f32 v202, v202, s0
	global_store_short v[192:193], v201, off offset:1024
	global_store_short v[192:193], v202, off offset:1088
	s_waitcnt vmcnt(30)
	v_mul_f32_e32 v201, v37, v171
	v_fma_f32 v201, v53, v170, -v201
	v_mul_f32_e32 v202, v53, v171
	v_fmac_f32_e32 v202, v37, v170
	v_cvt_pk_bf16_f32 v201, v201, s0
	v_cvt_pk_bf16_f32 v202, v202, s0
	global_store_short v[192:193], v201, off offset:1152
	global_store_short v[192:193], v202, off offset:1216
	s_waitcnt vmcnt(30)
	v_mul_f32_e32 v201, v38, v173
	v_fma_f32 v201, v54, v172, -v201
	v_mul_f32_e32 v202, v54, v173
	v_fmac_f32_e32 v202, v38, v172
	v_cvt_pk_bf16_f32 v201, v201, s0
	v_cvt_pk_bf16_f32 v202, v202, s0
	global_store_short v[192:193], v201, off offset:1280
	global_store_short v[192:193], v202, off offset:1344
	s_waitcnt vmcnt(30)
	v_mul_f32_e32 v201, v39, v175
	v_fma_f32 v201, v55, v174, -v201
	v_mul_f32_e32 v202, v55, v175
	v_fmac_f32_e32 v202, v39, v174
	v_cvt_pk_bf16_f32 v201, v201, s0
	v_cvt_pk_bf16_f32 v202, v202, s0
	global_store_short v[192:193], v201, off offset:1408
	global_store_short v[192:193], v202, off offset:1472
	s_waitcnt vmcnt(30)
	v_mul_f32_e32 v201, v40, v177
	v_fma_f32 v201, v56, v176, -v201
	v_mul_f32_e32 v202, v56, v177
	v_fmac_f32_e32 v202, v40, v176
	v_cvt_pk_bf16_f32 v201, v201, s0
	v_cvt_pk_bf16_f32 v202, v202, s0
	global_store_short v[192:193], v201, off offset:2048
	global_store_short v[192:193], v202, off offset:2112
	s_waitcnt vmcnt(30)
	v_mul_f32_e32 v201, v41, v179
	v_fma_f32 v201, v57, v178, -v201
	v_mul_f32_e32 v202, v57, v179
	v_fmac_f32_e32 v202, v41, v178
	v_cvt_pk_bf16_f32 v201, v201, s0
	v_cvt_pk_bf16_f32 v202, v202, s0
	global_store_short v[192:193], v201, off offset:2176
	global_store_short v[192:193], v202, off offset:2240
	s_waitcnt vmcnt(30)
	v_mul_f32_e32 v201, v42, v181
	v_fma_f32 v201, v58, v180, -v201
	v_mul_f32_e32 v202, v58, v181
	v_fmac_f32_e32 v202, v42, v180
	v_cvt_pk_bf16_f32 v201, v201, s0
	v_cvt_pk_bf16_f32 v202, v202, s0
	global_store_short v[192:193], v201, off offset:2304
	global_store_short v[192:193], v202, off offset:2368
	s_waitcnt vmcnt(30)
	v_mul_f32_e32 v201, v43, v183
	v_fma_f32 v201, v59, v182, -v201
	v_mul_f32_e32 v202, v59, v183
	v_fmac_f32_e32 v202, v43, v182
	v_cvt_pk_bf16_f32 v201, v201, s0
	v_cvt_pk_bf16_f32 v202, v202, s0
	global_store_short v[192:193], v201, off offset:2432
	global_store_short v[192:193], v202, off offset:2496
	s_waitcnt vmcnt(30)
	v_mul_f32_e32 v201, v44, v205
	v_fma_f32 v201, v60, v204, -v201
	v_mul_f32_e32 v202, v60, v205
	v_fmac_f32_e32 v202, v44, v204
	v_cvt_pk_bf16_f32 v201, v201, s0
	v_cvt_pk_bf16_f32 v202, v202, s0
	global_store_short v[192:193], v201, off offset:3072
	global_store_short v[192:193], v202, off offset:3136
	s_waitcnt vmcnt(30)
	v_mul_f32_e32 v201, v45, v207
	v_fma_f32 v201, v61, v206, -v201
	v_mul_f32_e32 v202, v61, v207
	v_fmac_f32_e32 v202, v45, v206
	v_cvt_pk_bf16_f32 v201, v201, s0
	v_cvt_pk_bf16_f32 v202, v202, s0
	global_store_short v[192:193], v201, off offset:3200
	global_store_short v[192:193], v202, off offset:3264
	s_waitcnt vmcnt(30)
	v_mul_f32_e32 v201, v46, v209
	v_fma_f32 v201, v62, v208, -v201
	v_mul_f32_e32 v202, v62, v209
	v_fmac_f32_e32 v202, v46, v208
	v_cvt_pk_bf16_f32 v201, v201, s0
	v_cvt_pk_bf16_f32 v202, v202, s0
	global_store_short v[192:193], v201, off offset:3328
	global_store_short v[192:193], v202, off offset:3392
	s_waitcnt vmcnt(30)
	v_mul_f32_e32 v201, v47, v211
	v_fma_f32 v201, v63, v210, -v201
	v_mul_f32_e32 v202, v63, v211
	v_fmac_f32_e32 v202, v47, v210
	v_cvt_pk_bf16_f32 v201, v201, s0
	v_cvt_pk_bf16_f32 v202, v202, s0
	global_store_short v[192:193], v201, off offset:3456
	global_store_short v[192:193], v202, off offset:3520
	v_add_co_u32_e32 v140, vcc, 0x6000, v132
	s_nop 1
	v_addc_co_u32_e32 v141, vcc, 0, v133, vcc
	v_add_co_u32_e32 v142, vcc, 0x7000, v132
	s_nop 1
	v_addc_co_u32_e32 v143, vcc, 0, v133, vcc
	global_load_dword v160, v[140:141], off
	global_load_dword v161, v[140:141], off offset:128
	global_load_dword v162, v[140:141], off offset:256
	global_load_dword v163, v[140:141], off offset:384
	global_load_dword v164, v[140:141], off offset:512
	global_load_dword v165, v[140:141], off offset:640
	global_load_dword v166, v[140:141], off offset:768
	global_load_dword v167, v[140:141], off offset:896
	global_load_dword v168, v[140:141], off offset:2048
	global_load_dword v169, v[140:141], off offset:2176
	global_load_dword v170, v[140:141], off offset:2304
	global_load_dword v171, v[140:141], off offset:2432
	global_load_dword v172, v[140:141], off offset:2560
	global_load_dword v173, v[140:141], off offset:2688
	global_load_dword v174, v[140:141], off offset:2816
	global_load_dword v175, v[140:141], off offset:2944
	global_load_dword v176, v[142:143], off
	global_load_dword v177, v[142:143], off offset:128
	global_load_dword v178, v[142:143], off offset:256
	global_load_dword v179, v[142:143], off offset:384
	global_load_dword v180, v[142:143], off offset:512
	global_load_dword v181, v[142:143], off offset:640
	global_load_dword v182, v[142:143], off offset:768
	global_load_dword v183, v[142:143], off offset:896
	global_load_dword v204, v[142:143], off offset:2048
	global_load_dword v205, v[142:143], off offset:2176
	global_load_dword v206, v[142:143], off offset:2304
	global_load_dword v207, v[142:143], off offset:2432
	global_load_dword v208, v[142:143], off offset:2560
	global_load_dword v209, v[142:143], off offset:2688
	global_load_dword v210, v[142:143], off offset:2816
	global_load_dword v211, v[142:143], off offset:2944
	v_add_co_u32_e32 v192, vcc, 0x3000, v134
	s_nop 1
	v_addc_co_u32_e32 v193, vcc, 0, v135, vcc
	s_waitcnt vmcnt(30)
	v_mul_f32_e32 v201, v0, v161
	v_fma_f32 v201, v16, v160, -v201
	v_mul_f32_e32 v202, v16, v161
	v_fmac_f32_e32 v202, v0, v160
	v_cvt_pk_bf16_f32 v201, v201, s0
	v_cvt_pk_bf16_f32 v202, v202, s0
	global_store_short v[192:193], v201, off
	global_store_short v[192:193], v202, off offset:64
	s_waitcnt vmcnt(30)
	v_mul_f32_e32 v201, v1, v163
	v_fma_f32 v201, v17, v162, -v201
	v_mul_f32_e32 v202, v17, v163
	v_fmac_f32_e32 v202, v1, v162
	v_cvt_pk_bf16_f32 v201, v201, s0
	v_cvt_pk_bf16_f32 v202, v202, s0
	global_store_short v[192:193], v201, off offset:128
	global_store_short v[192:193], v202, off offset:192
	s_waitcnt vmcnt(30)
	v_mul_f32_e32 v201, v2, v165
	v_fma_f32 v201, v18, v164, -v201
	v_mul_f32_e32 v202, v18, v165
	v_fmac_f32_e32 v202, v2, v164
	v_cvt_pk_bf16_f32 v201, v201, s0
	v_cvt_pk_bf16_f32 v202, v202, s0
	global_store_short v[192:193], v201, off offset:256
	global_store_short v[192:193], v202, off offset:320
	s_waitcnt vmcnt(30)
	v_mul_f32_e32 v201, v3, v167
	v_fma_f32 v201, v19, v166, -v201
	v_mul_f32_e32 v202, v19, v167
	v_fmac_f32_e32 v202, v3, v166
	v_cvt_pk_bf16_f32 v201, v201, s0
	v_cvt_pk_bf16_f32 v202, v202, s0
	global_store_short v[192:193], v201, off offset:384
	global_store_short v[192:193], v202, off offset:448
	s_waitcnt vmcnt(30)
	v_mul_f32_e32 v201, v4, v169
	v_fma_f32 v201, v20, v168, -v201
	v_mul_f32_e32 v202, v20, v169
	v_fmac_f32_e32 v202, v4, v168
	v_cvt_pk_bf16_f32 v201, v201, s0
	v_cvt_pk_bf16_f32 v202, v202, s0
	global_store_short v[192:193], v201, off offset:1024
	global_store_short v[192:193], v202, off offset:1088
	s_waitcnt vmcnt(30)
	v_mul_f32_e32 v201, v5, v171
	v_fma_f32 v201, v21, v170, -v201
	v_mul_f32_e32 v202, v21, v171
	v_fmac_f32_e32 v202, v5, v170
	v_cvt_pk_bf16_f32 v201, v201, s0
	v_cvt_pk_bf16_f32 v202, v202, s0
	global_store_short v[192:193], v201, off offset:1152
	global_store_short v[192:193], v202, off offset:1216
	s_waitcnt vmcnt(30)
	v_mul_f32_e32 v201, v6, v173
	v_fma_f32 v201, v22, v172, -v201
	v_mul_f32_e32 v202, v22, v173
	v_fmac_f32_e32 v202, v6, v172
	v_cvt_pk_bf16_f32 v201, v201, s0
	v_cvt_pk_bf16_f32 v202, v202, s0
	global_store_short v[192:193], v201, off offset:1280
	global_store_short v[192:193], v202, off offset:1344
	s_waitcnt vmcnt(30)
	v_mul_f32_e32 v201, v7, v175
	v_fma_f32 v201, v23, v174, -v201
	v_mul_f32_e32 v202, v23, v175
	v_fmac_f32_e32 v202, v7, v174
	v_cvt_pk_bf16_f32 v201, v201, s0
	v_cvt_pk_bf16_f32 v202, v202, s0
	global_store_short v[192:193], v201, off offset:1408
	global_store_short v[192:193], v202, off offset:1472
	s_waitcnt vmcnt(30)
	v_mul_f32_e32 v201, v8, v177
	v_fma_f32 v201, v24, v176, -v201
	v_mul_f32_e32 v202, v24, v177
	v_fmac_f32_e32 v202, v8, v176
	v_cvt_pk_bf16_f32 v201, v201, s0
	v_cvt_pk_bf16_f32 v202, v202, s0
	global_store_short v[192:193], v201, off offset:2048
	global_store_short v[192:193], v202, off offset:2112
	s_waitcnt vmcnt(30)
	v_mul_f32_e32 v201, v9, v179
	v_fma_f32 v201, v25, v178, -v201
	v_mul_f32_e32 v202, v25, v179
	v_fmac_f32_e32 v202, v9, v178
	v_cvt_pk_bf16_f32 v201, v201, s0
	v_cvt_pk_bf16_f32 v202, v202, s0
	global_store_short v[192:193], v201, off offset:2176
	global_store_short v[192:193], v202, off offset:2240
	s_waitcnt vmcnt(30)
	v_mul_f32_e32 v201, v10, v181
	v_fma_f32 v201, v26, v180, -v201
	v_mul_f32_e32 v202, v26, v181
	v_fmac_f32_e32 v202, v10, v180
	v_cvt_pk_bf16_f32 v201, v201, s0
	v_cvt_pk_bf16_f32 v202, v202, s0
	global_store_short v[192:193], v201, off offset:2304
	global_store_short v[192:193], v202, off offset:2368
	s_waitcnt vmcnt(30)
	v_mul_f32_e32 v201, v11, v183
	v_fma_f32 v201, v27, v182, -v201
	v_mul_f32_e32 v202, v27, v183
	v_fmac_f32_e32 v202, v11, v182
	v_cvt_pk_bf16_f32 v201, v201, s0
	v_cvt_pk_bf16_f32 v202, v202, s0
	global_store_short v[192:193], v201, off offset:2432
	global_store_short v[192:193], v202, off offset:2496
	s_waitcnt vmcnt(30)
	v_mul_f32_e32 v201, v12, v205
	v_fma_f32 v201, v28, v204, -v201
	v_mul_f32_e32 v202, v28, v205
	v_fmac_f32_e32 v202, v12, v204
	v_cvt_pk_bf16_f32 v201, v201, s0
	v_cvt_pk_bf16_f32 v202, v202, s0
	global_store_short v[192:193], v201, off offset:3072
	global_store_short v[192:193], v202, off offset:3136
	s_waitcnt vmcnt(30)
	v_mul_f32_e32 v201, v13, v207
	v_fma_f32 v201, v29, v206, -v201
	v_mul_f32_e32 v202, v29, v207
	v_fmac_f32_e32 v202, v13, v206
	v_cvt_pk_bf16_f32 v201, v201, s0
	v_cvt_pk_bf16_f32 v202, v202, s0
	global_store_short v[192:193], v201, off offset:3200
	global_store_short v[192:193], v202, off offset:3264
	s_waitcnt vmcnt(30)
	v_mul_f32_e32 v201, v14, v209
	v_fma_f32 v201, v30, v208, -v201
	v_mul_f32_e32 v202, v30, v209
	v_fmac_f32_e32 v202, v14, v208
	v_cvt_pk_bf16_f32 v201, v201, s0
	v_cvt_pk_bf16_f32 v202, v202, s0
	global_store_short v[192:193], v201, off offset:3328
	global_store_short v[192:193], v202, off offset:3392
	s_waitcnt vmcnt(30)
	v_mul_f32_e32 v201, v15, v211
	v_fma_f32 v201, v31, v210, -v201
	v_mul_f32_e32 v202, v31, v211
	v_fmac_f32_e32 v202, v15, v210
	v_cvt_pk_bf16_f32 v201, v201, s0
	v_cvt_pk_bf16_f32 v202, v202, s0
	global_store_short v[192:193], v201, off offset:3456
	global_store_short v[192:193], v202, off offset:3520

.LBB0_210:
	s_bfe_u32 s7, s6, 0x20004
	s_and_b32 s0, s6, 15
	s_lshl_b32 s8, s0, 5
	s_lshl_b32 s9, s7, 9
	s_or_b32 s8, s9, s8
	v_or_b32_e32 v0, s8, v178
	s_ashr_i32 s1, s6, 6
	s_lshl_b32 s17, s7, 22
	s_lshl_b32 s18, s1, 19
	s_or_b32 s17, s17, s18
	s_addk_i32 s17, 0x1000
	s_lshl_b32 s19, s7, 23
	s_lshl_b32 s18, s1, 20
	s_or_b32 s19, s19, s18
	s_lshl_b32 s18, s0, 12
	s_or_b32 s19, s19, s18
	s_mov_b64 s[20:21], 0x10000
	v_lshlrev_b32_e32 v186, 14, v0
	v_lshl_add_u32 v0, s7, 8, v179
	s_lshl_b32 s8, s1, 10
	v_ashrrev_i32_e32 v1, 31, v0
	s_ashr_i32 s9, s8, 31
	v_lshlrev_b64 v[0:1], 14, v[0:1]
	s_lshl_b64 s[8:9], s[8:9], 1
	v_lshl_add_u64 v[0:1], s[10:11], 0, v[0:1]
	v_lshl_add_u64 v[0:1], v[0:1], 0, s[8:9]
	v_mov_b32_e32 v161, v187
	v_lshl_add_u64 v[166:167], v[0:1], 0, v[160:161]
	v_lshrrev_b32_e32 v188, 6, v152
	v_and_b32_e32 v190, 63, v152
	v_lshlrev_b32_e32 v188, 13, v188
	v_lshl_or_b32 v188, v190, 4, v188
	v_add_u32_e32 v220, s17, v188
	v_mov_b32_e32 v221, 0
	v_lshl_add_u64 v[220:221], s[10:11], 0, v[220:221]
	v_add_co_u32_e32 v222, vcc, 0x8000, v220
	s_nop 1
	v_addc_co_u32_e32 v223, vcc, 0, v221, vcc
	v_add_co_u32_e32 v224, vcc, 0x8000, v222
	s_nop 1
	v_addc_co_u32_e32 v225, vcc, 0, v223, vcc
	v_add_co_u32_e32 v226, vcc, 0x8000, v224
	s_nop 1
	v_addc_co_u32_e32 v227, vcc, 0, v225, vcc
	v_add_co_u32_e32 v228, vcc, 0x8000, v226
	s_nop 1
	v_addc_co_u32_e32 v229, vcc, 0, v227, vcc
	v_add_co_u32_e32 v230, vcc, 0x8000, v228
	s_nop 1
	v_addc_co_u32_e32 v231, vcc, 0, v229, vcc
	v_add_co_u32_e32 v232, vcc, 0x8000, v230
	s_nop 1
	v_addc_co_u32_e32 v233, vcc, 0, v231, vcc
	v_add_co_u32_e32 v234, vcc, 0x8000, v232
	s_nop 1
	v_addc_co_u32_e32 v235, vcc, 0, v233, vcc
	v_add_co_u32_e32 v236, vcc, 0x8000, v234
	s_nop 1
	v_addc_co_u32_e32 v237, vcc, 0, v235, vcc
	v_add_co_u32_e32 v238, vcc, 0x8000, v236
	s_nop 1
	v_addc_co_u32_e32 v239, vcc, 0, v237, vcc
	v_add_co_u32_e32 v240, vcc, 0x8000, v238
	s_nop 1
	v_addc_co_u32_e32 v241, vcc, 0, v239, vcc
	v_add_co_u32_e32 v244, vcc, 0x8000, v240
	s_nop 1
	v_addc_co_u32_e32 v245, vcc, 0, v241, vcc
	v_add_co_u32_e32 v246, vcc, 0x8000, v244
	s_nop 1
	v_addc_co_u32_e32 v247, vcc, 0, v245, vcc
	v_add_co_u32_e32 v248, vcc, 0x8000, v246
	s_nop 1
	v_addc_co_u32_e32 v249, vcc, 0, v247, vcc
	v_add_co_u32_e32 v250, vcc, 0x8000, v248
	s_nop 1
	v_addc_co_u32_e32 v251, vcc, 0, v249, vcc
	v_add_co_u32_e32 v252, vcc, 0x8000, v250
	s_nop 1
	v_addc_co_u32_e32 v253, vcc, 0, v251, vcc
	global_load_dwordx4 v[0:3], v[220:221], off offset:-4096
	v_lshl_add_u64 v[4:5], s[2:3], 0, v[186:187]
	v_lshl_add_u64 v[4:5], v[4:5], 0, s[8:9]
	v_lshlrev_b32_e32 v188, 4, v190
	v_add_u32_e32 v168, s19, v188
	v_mov_b32_e32 v169, 0
	v_lshl_add_u64 v[168:169], s[2:3], 0, v[168:169]
	global_load_dwordx4 v[4:7], v[168:169], off
	v_add_co_u32_e32 v164, vcc, s79, v166
	s_lshl_b32 s8, s1, 4
	s_nop 0
	v_addc_co_u32_e32 v165, vcc, 0, v167, vcc
	global_load_dwordx4 v[8:11], v[220:221], off
	global_load_dwordx4 v[32:35], v[220:221], off offset:-3072
	global_load_dwordx4 v[36:39], v[168:169], off offset:1024
	global_load_dwordx4 v[40:43], v[220:221], off offset:1024
	global_load_dwordx4 v[44:47], v[220:221], off offset:-2048
	global_load_dwordx4 v[52:55], v[168:169], off offset:2048
	global_load_dwordx4 v[56:59], v[220:221], off offset:2048
	global_load_dwordx4 v[60:63], v[220:221], off offset:-1024
	global_load_dwordx4 v[64:67], v[168:169], off offset:3072
	v_lshl_add_u64 v[168:169], v[168:169], 0, s[20:21]
	s_ashr_i32 s9, s8, 31
	s_lshl_b64 s[8:9], s[8:9], 12
	s_add_u32 s14, s4, s8
	s_addc_u32 s15, s5, s9
	s_lshl_b32 s16, s7, 10
	global_load_dwordx4 v[68:71], v[220:221], off offset:3072
	s_add_u32 s14, s14, s16
	s_addc_u32 s15, s15, 0
	v_mov_b32_e32 v163, v187
	v_lshl_add_u64 v[12:13], v[154:155], 2, s[14:15]
	v_lshl_add_u64 v[170:171], v[12:13], 0, v[162:163]
	global_load_dwordx4 v[72:75], v[170:171], off offset:96
	global_load_dwordx4 v[76:79], v[170:171], off offset:64
	global_load_dwordx4 v[80:83], v[222:223], off offset:-4096
	global_load_dwordx4 v[84:87], v[170:171], off offset:32
	global_load_dwordx4 v[88:91], v[170:171], off
	global_load_dwordx4 v[92:95], v[168:169], off
	global_load_dwordx4 v[96:99], v[170:171], off offset:224
	global_load_dwordx4 v[180:183], v[170:171], off offset:192
	global_load_dwordx4 v[192:195], v[222:223], off
	global_load_dwordx4 v[196:199], v[170:171], off offset:160
	global_load_dwordx4 v[200:203], v[170:171], off offset:128
	global_load_dwordx4 v[204:207], v[222:223], off offset:-3072
	global_load_dwordx4 v[208:211], v[168:169], off offset:1024
	s_movk_i32 s14, 0x3000
	s_lshl_b32 s1, s1, 2
	s_or_b32 s7, s1, s7
	s_lshl_b32 s1, s7, 4
	s_waitcnt vmcnt(23) lgkmcnt(0)
	v_mfma_f32_32x32x16_bf16 v[16:31], v[0:3], v[4:7], 0
	s_waitcnt vmcnt(22)
	v_mfma_f32_32x32x16_bf16 v[0:15], v[8:11], v[4:7], 0
	s_waitcnt vmcnt(20)
	v_mfma_f32_32x32x16_bf16 v[16:31], v[32:35], v[36:39], v[16:31]
	global_load_dwordx4 v[32:35], v[222:223], off offset:1024
	s_waitcnt vmcnt(20)
	v_mfma_f32_32x32x16_bf16 v[0:15], v[40:43], v[36:39], v[0:15]
	global_load_dwordx4 v[40:43], v[222:223], off offset:-2048
	global_load_dwordx4 v[212:215], v[168:169], off offset:2048
	global_load_dwordx4 v[216:219], v[222:223], off offset:2048
	global_load_dwordx4 v[48:51], v[222:223], off offset:-1024
	global_load_dwordx4 v[108:111], v[224:225], off offset:-4096
	global_load_dwordx4 v[116:119], v[168:169], off offset:3072
	v_lshl_add_u64 v[168:169], v[168:169], 0, s[20:21]
	global_load_dwordx4 v[124:127], v[222:223], off offset:3072
	global_load_dwordx4 v[100:103], v[224:225], off
	global_load_dwordx4 v[104:107], v[168:169], off
	v_add_co_u32_e32 v36, vcc, s29, v170
	s_nop 1
	v_addc_co_u32_e32 v37, vcc, 0, v171, vcc
	s_waitcnt vmcnt(27)
	v_mfma_f32_32x32x16_bf16 v[16:31], v[44:47], v[52:55], v[16:31]
	v_add_co_u32_e32 v174, vcc, s76, v170
	s_nop 1
	v_addc_co_u32_e32 v175, vcc, 0, v171, vcc
	global_load_dwordx4 v[128:131], v[174:175], off offset:-4096
	global_load_dwordx4 v[136:139], v[36:37], off offset:32
	global_load_dwordx4 v[144:147], v[36:37], off offset:64
	global_load_dwordx4 v[148:151], v[36:37], off offset:96
	global_load_dwordx4 v[112:115], v[36:37], off offset:128
	global_load_dwordx4 v[120:123], v[36:37], off offset:160
	global_load_dwordx4 v[132:135], v[36:37], off offset:192
	global_load_dwordx4 v[140:143], v[36:37], off offset:224
	s_waitcnt vmcnt(32)
	v_mfma_f32_32x32x16_bf16 v[16:31], v[60:63], v[64:67], v[16:31]
	v_add_co_u32_e32 v176, vcc, s14, v170
	s_mov_b32 s14, 0xf000
	s_nop 0
	v_addc_co_u32_e32 v177, vcc, 0, v171, vcc
	v_add_co_u32_e32 v172, vcc, s14, v170
	v_mfma_f32_32x32x16_bf16 v[0:15], v[56:59], v[52:55], v[0:15]
	s_waitcnt vmcnt(30)
	s_nop 4
	v_mul_f32_e64 v30, v74, v30
	v_mul_f32_e64 v31, v75, v31
	v_mul_f32_e64 v28, v72, v28
	v_mul_f32_e64 v29, v73, v29
	global_load_dwordx4 v[36:39], v[224:225], off offset:-3072
	global_load_dwordx4 v[72:75], v[168:169], off offset:1024
	s_waitcnt vmcnt(31)
	v_pk_mul_f32 v[26:27], v[78:79], v[26:27]
	v_pk_mul_f32 v[24:25], v[76:77], v[24:25]
	global_load_dwordx4 v[76:79], v[224:225], off offset:1024
	s_waitcnt vmcnt(30)
	v_pk_mul_f32 v[22:23], v[86:87], v[22:23]
	v_mfma_f32_32x32x16_bf16 v[0:15], v[68:71], v[64:67], v[0:15]
	global_load_dwordx4 v[68:71], v[224:225], off offset:-2048
	global_load_dwordx4 v[52:55], v[168:169], off offset:2048
	global_load_dwordx4 v[64:67], v[224:225], off offset:-1024
	global_load_dwordx4 v[44:47], v[168:169], off offset:3072
	v_lshl_add_u64 v[168:169], v[168:169], 0, s[20:21]
	global_load_dwordx4 v[60:63], v[224:225], off offset:2048
	v_pk_mul_f32 v[20:21], v[84:85], v[20:21]
	s_waitcnt vmcnt(34)
	v_pk_mul_f32 v[18:19], v[90:91], v[18:19]
	v_pk_mul_f32 v[16:17], v[88:89], v[16:17]
	v_addc_co_u32_e32 v173, vcc, 0, v171, vcc
	s_waitcnt vmcnt(33)
	v_mfma_f32_32x32x16_bf16 v[16:31], v[80:83], v[92:95], v[16:31]
	s_waitcnt vmcnt(32)
	v_mul_f32_e64 v14, v98, v14
	v_mul_f32_e64 v15, v99, v15
	v_mul_f32_e64 v12, v96, v12
	v_mul_f32_e64 v13, v97, v13
	s_waitcnt vmcnt(31)
	v_pk_mul_f32 v[10:11], v[182:183], v[10:11]
	v_pk_mul_f32 v[8:9], v[180:181], v[8:9]
	s_waitcnt vmcnt(29)
	v_pk_mul_f32 v[6:7], v[198:199], v[6:7]
	v_pk_mul_f32 v[4:5], v[196:197], v[4:5]
	s_waitcnt vmcnt(28)
	v_pk_mul_f32 v[2:3], v[202:203], v[2:3]
	v_pk_mul_f32 v[0:1], v[200:201], v[0:1]
	s_waitcnt vmcnt(26)
	v_mfma_f32_32x32x16_bf16 v[16:31], v[204:207], v[208:211], v[16:31]
	s_movk_i32 s14, 0x4000
	v_mfma_f32_32x32x16_bf16 v[0:15], v[192:195], v[92:95], v[0:15]
	s_waitcnt vmcnt(25)
	v_mfma_f32_32x32x16_bf16 v[0:15], v[32:35], v[208:211], v[0:15]
	s_waitcnt vmcnt(23)
	v_mfma_f32_32x32x16_bf16 v[16:31], v[40:43], v[212:215], v[16:31]
	global_load_dwordx4 v[56:59], v[224:225], off offset:3072
	global_load_dwordx4 v[40:43], v[226:227], off offset:-4096
	global_load_dwordx4 v[32:35], v[168:169], off
	s_waitcnt vmcnt(25)
	v_mfma_f32_32x32x16_bf16 v[0:15], v[216:219], v[212:215], v[0:15]
	s_waitcnt vmcnt(22)
	v_mfma_f32_32x32x16_bf16 v[16:31], v[48:51], v[116:119], v[16:31]
	global_load_dwordx4 v[92:95], v[174:175], off offset:64
	global_load_dwordx4 v[96:99], v[174:175], off offset:96
	global_load_dwordx4 v[84:87], v[174:175], off
	global_load_dwordx4 v[88:91], v[174:175], off offset:32
	global_load_dwordx4 v[80:83], v[176:177], off offset:32
	global_load_dwordx4 v[48:51], v[172:173], off offset:224
	s_waitcnt vmcnt(21)
	s_nop 4
	v_pk_mul_f32 v[30:31], v[150:151], v[30:31]
	v_mfma_f32_32x32x16_bf16 v[0:15], v[124:127], v[116:119], v[0:15]
	v_mul_f32_e64 v28, v148, v28
	v_mul_f32_e64 v29, v149, v29
	v_mul_f32_e64 v26, v146, v26
	v_mul_f32_e64 v27, v147, v27
	v_mul_f32_e64 v24, v144, v24
	v_mul_f32_e64 v25, v145, v25
	v_pk_mul_f32 v[22:23], v[138:139], v[22:23]
	v_pk_mul_f32 v[20:21], v[136:137], v[20:21]
	v_pk_mul_f32 v[18:19], v[130:131], v[18:19]
	v_pk_mul_f32 v[16:17], v[128:129], v[16:17]
	s_waitcnt vmcnt(17)
	s_nop 0
	v_pk_mul_f32 v[14:15], v[142:143], v[14:15]
	v_pk_mul_f32 v[12:13], v[140:141], v[12:13]
	v_mfma_f32_32x32x16_bf16 v[16:31], v[108:111], v[104:107], v[16:31]
	v_mul_f32_e64 v10, v134, v10
	v_mul_f32_e64 v11, v135, v11
	v_mul_f32_e64 v8, v132, v8
	v_mul_f32_e64 v9, v133, v9
	v_mul_f32_e64 v6, v122, v6
	v_mul_f32_e64 v7, v123, v7
	v_pk_mul_f32 v[4:5], v[120:121], v[4:5]
	v_pk_mul_f32 v[2:3], v[114:115], v[2:3]
	v_pk_mul_f32 v[0:1], v[112:113], v[0:1]
	v_add_co_u32_e32 v140, vcc, s14, v170
	s_nop 0
	v_mfma_f32_32x32x16_bf16 v[0:15], v[100:103], v[104:107], v[0:15]
	global_load_dwordx4 v[100:103], v[226:227], off offset:-3072
	global_load_dwordx4 v[104:107], v[168:169], off offset:1024
	v_addc_co_u32_e32 v141, vcc, 0, v171, vcc
	s_movk_i32 s14, 0x5000
	s_waitcnt vmcnt(17)
	v_mfma_f32_32x32x16_bf16 v[16:31], v[36:39], v[72:75], v[16:31]
	global_load_dwordx4 v[36:39], v[226:227], off offset:-2048
	global_load_dwordx4 v[108:111], v[168:169], off offset:2048
	s_waitcnt vmcnt(16)
	v_mfma_f32_32x32x16_bf16 v[16:31], v[68:71], v[52:55], v[16:31]
	v_mfma_f32_32x32x16_bf16 v[0:15], v[76:79], v[72:75], v[0:15]
	global_load_dwordx4 v[72:75], v[226:227], off offset:-1024
	global_load_dwordx4 v[76:79], v[168:169], off offset:3072
	v_lshl_add_u64 v[168:169], v[168:169], 0, s[20:21]
	global_load_dwordx4 v[112:115], v[174:175], off offset:224
	global_load_dwordx4 v[116:119], v[174:175], off offset:192
	global_load_dwordx4 v[120:123], v[174:175], off offset:160
	global_load_dwordx4 v[68:71], v[226:227], off
	global_load_dwordx4 v[124:127], v[174:175], off offset:128
	s_waitcnt vmcnt(21)
	v_mfma_f32_32x32x16_bf16 v[16:31], v[64:67], v[44:47], v[16:31]
	global_load_dwordx4 v[64:67], v[226:227], off offset:1024
	s_waitcnt vmcnt(21)
	v_mfma_f32_32x32x16_bf16 v[0:15], v[60:63], v[52:55], v[0:15]
	global_load_dwordx4 v[52:55], v[226:227], off offset:2048
	global_load_dwordx4 v[60:63], v[226:227], off offset:3072
	s_waitcnt vmcnt(19)
	s_nop 5
	v_mul_f32_e64 v26, v94, v26
	v_mul_f32_e64 v27, v95, v27
	v_mfma_f32_32x32x16_bf16 v[0:15], v[56:59], v[44:47], v[0:15]
	global_load_dwordx4 v[44:47], v[228:229], off offset:-4096
	s_waitcnt vmcnt(19)
	v_mul_f32_e64 v30, v98, v30
	v_mul_f32_e64 v31, v99, v31
	v_mul_f32_e64 v28, v96, v28
	v_mul_f32_e64 v29, v97, v29
	v_pk_mul_f32 v[24:25], v[92:93], v[24:25]
	global_load_dwordx4 v[56:59], v[176:177], off offset:64
	global_load_dwordx4 v[92:95], v[176:177], off offset:96
	s_waitcnt vmcnt(19)
	v_pk_mul_f32 v[22:23], v[90:91], v[22:23]
	v_pk_mul_f32 v[20:21], v[88:89], v[20:21]
	global_load_dwordx4 v[88:91], v[140:141], off offset:-4096
	v_pk_mul_f32 v[18:19], v[86:87], v[18:19]
	v_pk_mul_f32 v[16:17], v[84:85], v[16:17]
	s_waitcnt vmcnt(11)
	v_pk_mul_f32 v[14:15], v[114:115], v[14:15]
	v_mfma_f32_32x32x16_bf16 v[16:31], v[40:43], v[32:35], v[16:31]
	global_load_dwordx4 v[40:43], v[168:169], off
	global_load_dwordx4 v[84:87], v[228:229], off offset:-3072
	global_load_dwordx4 v[96:99], v[168:169], off offset:1024
	v_mul_f32_e64 v12, v112, v12
	v_mul_f32_e64 v13, v113, v13
	s_waitcnt vmcnt(13)
	v_pk_mul_f32 v[10:11], v[118:119], v[10:11]
	v_pk_mul_f32 v[8:9], v[116:117], v[8:9]
	s_waitcnt vmcnt(12)
	v_pk_mul_f32 v[6:7], v[122:123], v[6:7]
	v_pk_mul_f32 v[4:5], v[120:121], v[4:5]
	v_mfma_f32_32x32x16_bf16 v[16:31], v[100:103], v[104:107], v[16:31]
	s_waitcnt vmcnt(10)
	v_mul_f32_e64 v2, v126, v2
	v_mul_f32_e64 v3, v127, v3
	v_mul_f32_e64 v0, v124, v0
	v_mul_f32_e64 v1, v125, v1
	v_mfma_f32_32x32x16_bf16 v[16:31], v[36:39], v[108:111], v[16:31]
	global_load_dwordx4 v[36:39], v[228:229], off offset:-2048
	global_load_dwordx4 v[100:103], v[168:169], off offset:2048
	global_load_dwordx4 v[128:131], v[228:229], off offset:-1024
	global_load_dwordx4 v[132:135], v[168:169], off offset:3072
	v_lshl_add_u64 v[168:169], v[168:169], 0, s[20:21]
	global_load_dwordx4 v[136:139], v[228:229], off
	v_mfma_f32_32x32x16_bf16 v[0:15], v[68:71], v[32:35], v[0:15]
	v_mfma_f32_32x32x16_bf16 v[16:31], v[72:75], v[76:79], v[16:31]
	global_load_dwordx4 v[72:75], v[176:177], off offset:192
	global_load_dwordx4 v[112:115], v[176:177], off offset:224
	global_load_dwordx4 v[32:35], v[176:177], off offset:160
	global_load_dwordx4 v[68:71], v[176:177], off offset:128
	s_waitcnt vmcnt(18)
	v_mfma_f32_32x32x16_bf16 v[0:15], v[64:67], v[104:107], v[0:15]
	global_load_dwordx4 v[64:67], v[228:229], off offset:1024
	s_waitcnt vmcnt(14)
	s_nop 3
	v_mul_f32_e64 v30, v94, v30
	v_mul_f32_e64 v31, v95, v31
	v_mul_f32_e64 v28, v92, v28
	v_mul_f32_e64 v29, v93, v29
	v_pk_mul_f32 v[26:27], v[58:59], v[26:27]
	v_pk_mul_f32 v[24:25], v[56:57], v[24:25]
	v_pk_mul_f32 v[22:23], v[82:83], v[22:23]
	v_pk_mul_f32 v[20:21], v[80:81], v[20:21]
	v_mfma_f32_32x32x16_bf16 v[0:15], v[52:55], v[108:111], v[0:15]
	global_load_dwordx4 v[52:55], v[228:229], off offset:2048
	global_load_dwordx4 v[104:107], v[228:229], off offset:3072
	s_waitcnt vmcnt(15)
	v_mul_f32_e64 v18, v90, v18
	v_mul_f32_e64 v19, v91, v19
	v_pk_mul_f32 v[16:17], v[88:89], v[16:17]
	global_load_dwordx4 v[56:59], v[140:141], off
	s_waitcnt vmcnt(15)
	v_mfma_f32_32x32x16_bf16 v[16:31], v[44:47], v[40:43], v[16:31]
	v_mfma_f32_32x32x16_bf16 v[0:15], v[60:63], v[76:79], v[0:15]
	global_load_dwordx4 v[60:63], v[140:141], off offset:96
	global_load_dwordx4 v[76:79], v[140:141], off offset:64
	global_load_dwordx4 v[44:47], v[140:141], off offset:32
	global_load_dwordx4 v[80:83], v[230:231], off offset:-4096
	s_waitcnt vmcnt(17)
	v_mfma_f32_32x32x16_bf16 v[16:31], v[84:87], v[96:99], v[16:31]
	global_load_dwordx4 v[84:87], v[168:169], off
	global_load_dwordx4 v[88:91], v[230:231], off offset:-3072
	s_waitcnt vmcnt(13)
	s_nop 2
	v_mul_f32_e64 v10, v74, v10
	v_mul_f32_e64 v11, v75, v11
	v_mfma_f32_32x32x16_bf16 v[16:31], v[36:39], v[100:103], v[16:31]
	global_load_dwordx4 v[36:39], v[168:169], off offset:1024
	global_load_dwordx4 v[92:95], v[230:231], off offset:-2048
	global_load_dwordx4 v[108:111], v[168:169], off offset:2048
	global_load_dwordx4 v[116:119], v[230:231], off offset:-1024
	s_waitcnt vmcnt(16)
	v_pk_mul_f32 v[14:15], v[114:115], v[14:15]
	v_pk_mul_f32 v[12:13], v[112:113], v[12:13]
	v_pk_mul_f32 v[8:9], v[72:73], v[8:9]
	s_waitcnt vmcnt(15)
	v_pk_mul_f32 v[6:7], v[34:35], v[6:7]
	v_pk_mul_f32 v[4:5], v[32:33], v[4:5]
	s_waitcnt vmcnt(14)
	v_pk_mul_f32 v[2:3], v[70:71], v[2:3]
	v_pk_mul_f32 v[0:1], v[68:69], v[0:1]
	v_mfma_f32_32x32x16_bf16 v[16:31], v[128:131], v[132:135], v[16:31]
	s_nop 0
	v_mfma_f32_32x32x16_bf16 v[0:15], v[136:139], v[40:43], v[0:15]
	global_load_dwordx4 v[32:35], v[168:169], off offset:3072
	v_lshl_add_u64 v[168:169], v[168:169], 0, s[20:21]
	global_load_dwordx4 v[40:43], v[140:141], off offset:224
	global_load_dwordx4 v[68:71], v[140:141], off offset:192
	global_load_dwordx4 v[72:75], v[140:141], off offset:160
	s_waitcnt vmcnt(14)
	s_nop 4
	v_pk_mul_f32 v[18:19], v[58:59], v[18:19]
	v_pk_mul_f32 v[16:17], v[56:57], v[16:17]
	s_waitcnt vmcnt(13)
	v_pk_mul_f32 v[30:31], v[62:63], v[30:31]
	v_mfma_f32_32x32x16_bf16 v[0:15], v[64:67], v[96:99], v[0:15]
	global_load_dwordx4 v[64:67], v[230:231], off
	global_load_dwordx4 v[96:99], v[140:141], off offset:128
	v_add_co_u32_e32 v140, vcc, s14, v170
	s_movk_i32 s14, 0x6000
	s_nop 0
	v_addc_co_u32_e32 v141, vcc, 0, v171, vcc
	v_add_co_u32_e32 v142, vcc, s14, v170
	v_mfma_f32_32x32x16_bf16 v[0:15], v[52:55], v[100:103], v[0:15]
	global_load_dwordx4 v[52:55], v[230:231], off offset:1024
	global_load_dwordx4 v[100:103], v[230:231], off offset:2048
	global_load_dwordx4 v[112:115], v[230:231], off offset:3072
	v_addc_co_u32_e32 v143, vcc, 0, v171, vcc
	v_mul_f32_e64 v28, v60, v28
	v_mul_f32_e64 v29, v61, v29
	s_waitcnt vmcnt(17)
	v_pk_mul_f32 v[26:27], v[78:79], v[26:27]
	v_pk_mul_f32 v[24:25], v[76:77], v[24:25]
	s_waitcnt vmcnt(16)
	v_pk_mul_f32 v[22:23], v[46:47], v[22:23]
	v_mfma_f32_32x32x16_bf16 v[0:15], v[104:107], v[132:135], v[0:15]
	global_load_dwordx4 v[104:107], v[232:233], off offset:-4096
	v_mul_f32_e64 v20, v44, v20
	v_mul_f32_e64 v21, v45, v21
	global_load_dwordx4 v[44:47], v[140:141], off offset:96
	global_load_dwordx4 v[56:59], v[140:141], off offset:32
	global_load_dwordx4 v[60:63], v[140:141], off offset:64
	global_load_dwordx4 v[76:79], v[142:143], off offset:-4096
	s_movk_i32 s14, 0x7000
	v_add_co_u32_e32 v174, vcc, s14, v170
	s_waitcnt vmcnt(19)
	v_mfma_f32_32x32x16_bf16 v[16:31], v[80:83], v[84:87], v[16:31]
	global_load_dwordx4 v[80:83], v[168:169], off
	global_load_dwordx4 v[120:123], v[232:233], off offset:-3072
	v_addc_co_u32_e32 v175, vcc, 0, v171, vcc
	s_mov_b32 s14, 0x8000
	v_add_co_u32_e32 v176, vcc, s14, v170
	s_mov_b32 s14, 0x9000
	s_waitcnt vmcnt(19)
	v_mfma_f32_32x32x16_bf16 v[16:31], v[88:91], v[36:39], v[16:31]
	global_load_dwordx4 v[88:91], v[168:169], off offset:1024
	global_load_dwordx4 v[124:127], v[232:233], off offset:-2048
	v_addc_co_u32_e32 v177, vcc, 0, v171, vcc
	s_waitcnt vmcnt(16)
	v_mul_f32_e64 v14, v42, v14
	v_mul_f32_e64 v15, v43, v15
	v_pk_mul_f32 v[12:13], v[40:41], v[12:13]
	s_waitcnt vmcnt(15)
	v_pk_mul_f32 v[10:11], v[70:71], v[10:11]
	v_mfma_f32_32x32x16_bf16 v[16:31], v[92:95], v[108:111], v[16:31]
	v_mul_f32_e64 v8, v68, v8
	v_mul_f32_e64 v9, v69, v9
	s_waitcnt vmcnt(14)
	v_mul_f32_e64 v6, v74, v6
	v_mul_f32_e64 v7, v75, v7
	v_pk_mul_f32 v[4:5], v[72:73], v[4:5]
	global_load_dwordx4 v[92:95], v[168:169], off offset:2048
	global_load_dwordx4 v[128:131], v[232:233], off offset:-1024
	global_load_dwordx4 v[132:135], v[168:169], off offset:3072
	v_lshl_add_u64 v[168:169], v[168:169], 0, s[20:21]
	global_load_dwordx4 v[136:139], v[232:233], off
	s_waitcnt vmcnt(16)
	v_pk_mul_f32 v[2:3], v[98:99], v[2:3]
	v_pk_mul_f32 v[0:1], v[96:97], v[0:1]
	v_mfma_f32_32x32x16_bf16 v[16:31], v[116:119], v[32:35], v[16:31]
	global_load_dwordx4 v[40:43], v[140:141], off offset:224
	global_load_dwordx4 v[68:71], v[140:141], off offset:160
	global_load_dwordx4 v[116:119], v[140:141], off offset:192
	v_mfma_f32_32x32x16_bf16 v[0:15], v[64:67], v[84:87], v[0:15]
	global_load_dwordx4 v[64:67], v[140:141], off offset:128
	s_waitcnt vmcnt(15)
	s_nop 5
	v_mul_f32_e64 v30, v46, v30
	v_mul_f32_e64 v31, v47, v31
	v_mfma_f32_32x32x16_bf16 v[0:15], v[52:55], v[36:39], v[0:15]
	global_load_dwordx4 v[36:39], v[232:233], off offset:1024
	global_load_dwordx4 v[52:55], v[232:233], off offset:2048
	global_load_dwordx4 v[72:75], v[232:233], off offset:3072
	v_mul_f32_e64 v28, v44, v28
	v_mul_f32_e64 v29, v45, v29
	s_waitcnt vmcnt(16)
	v_pk_mul_f32 v[26:27], v[62:63], v[26:27]
	v_pk_mul_f32 v[24:25], v[60:61], v[24:25]
	v_pk_mul_f32 v[22:23], v[58:59], v[22:23]
	v_pk_mul_f32 v[20:21], v[56:57], v[20:21]
	v_mfma_f32_32x32x16_bf16 v[0:15], v[100:103], v[108:111], v[0:15]
	s_waitcnt vmcnt(15)
	v_mul_f32_e64 v18, v78, v18
	v_mul_f32_e64 v19, v79, v19
	v_mul_f32_e64 v16, v76, v16
	v_mul_f32_e64 v17, v77, v17
	v_mfma_f32_32x32x16_bf16 v[0:15], v[112:115], v[32:35], v[0:15]
	global_load_dwordx4 v[32:35], v[142:143], off offset:96
	global_load_dwordx4 v[44:47], v[142:143], off offset:64
	global_load_dwordx4 v[56:59], v[234:235], off offset:-4096
	global_load_dwordx4 v[60:63], v[142:143], off offset:32
	global_load_dwordx4 v[76:79], v[142:143], off
	global_load_dwordx4 v[84:87], v[168:169], off
	global_load_dwordx4 v[96:99], v[234:235], off offset:-3072
	s_waitcnt vmcnt(13)
	s_nop 3
	v_pk_mul_f32 v[14:15], v[42:43], v[14:15]
	v_mfma_f32_32x32x16_bf16 v[16:31], v[104:107], v[80:83], v[16:31]
	v_mul_f32_e64 v12, v40, v12
	v_mul_f32_e64 v13, v41, v13
	s_waitcnt vmcnt(11)
	v_mul_f32_e64 v10, v118, v10
	v_mul_f32_e64 v11, v119, v11
	v_pk_mul_f32 v[8:9], v[116:117], v[8:9]
	v_pk_mul_f32 v[6:7], v[70:71], v[6:7]
	v_pk_mul_f32 v[4:5], v[68:69], v[4:5]
	s_waitcnt vmcnt(10)
	v_pk_mul_f32 v[2:3], v[66:67], v[2:3]
	v_mfma_f32_32x32x16_bf16 v[16:31], v[120:123], v[88:91], v[16:31]
	global_load_dwordx4 v[100:103], v[168:169], off offset:1024
	global_load_dwordx4 v[104:107], v[234:235], off offset:-2048
	global_load_dwordx4 v[108:111], v[168:169], off offset:2048
	global_load_dwordx4 v[112:115], v[168:169], off offset:3072
	v_lshl_add_u64 v[168:169], v[168:169], 0, s[20:21]
	global_load_dwordx4 v[120:123], v[234:235], off offset:-1024
	v_pk_mul_f32 v[0:1], v[64:65], v[0:1]
	s_nop 1
	v_mfma_f32_32x32x16_bf16 v[0:15], v[136:139], v[80:83], v[0:15]
	v_mfma_f32_32x32x16_bf16 v[16:31], v[124:127], v[92:95], v[16:31]
	global_load_dwordx4 v[124:127], v[174:175], off offset:32
	global_load_dwordx4 v[40:43], v[142:143], off offset:192
	global_load_dwordx4 v[116:119], v[142:143], off offset:224
	global_load_dwordx4 v[64:67], v[142:143], off offset:160
	global_load_dwordx4 v[68:71], v[234:235], off
	global_load_dwordx4 v[80:83], v[142:143], off offset:128
	s_waitcnt vmcnt(20)
	v_mfma_f32_32x32x16_bf16 v[0:15], v[36:39], v[88:91], v[0:15]
	global_load_dwordx4 v[88:91], v[234:235], off offset:1024
	s_waitcnt vmcnt(20)
	v_mfma_f32_32x32x16_bf16 v[0:15], v[52:55], v[92:95], v[0:15]
	global_load_dwordx4 v[52:55], v[234:235], off offset:2048
	global_load_dwordx4 v[92:95], v[234:235], off offset:3072
	v_mfma_f32_32x32x16_bf16 v[16:31], v[128:131], v[132:135], v[16:31]
	s_waitcnt vmcnt(21)
	v_mfma_f32_32x32x16_bf16 v[0:15], v[72:75], v[132:135], v[0:15]
	s_waitcnt vmcnt(20)
	s_nop 8
	v_mul_f32_e64 v30, v34, v30
	v_mul_f32_e64 v31, v35, v31
	v_mul_f32_e64 v28, v32, v28
	v_mul_f32_e64 v29, v33, v29
	s_waitcnt vmcnt(19)
	v_pk_mul_f32 v[26:27], v[46:47], v[26:27]
	v_pk_mul_f32 v[24:25], v[44:45], v[24:25]
	s_waitcnt vmcnt(17)
	v_pk_mul_f32 v[22:23], v[62:63], v[22:23]
	v_pk_mul_f32 v[20:21], v[60:61], v[20:21]
	s_waitcnt vmcnt(16)
	v_pk_mul_f32 v[18:19], v[78:79], v[18:19]
	v_pk_mul_f32 v[16:17], v[76:77], v[16:17]
	s_waitcnt vmcnt(7)
	v_pk_mul_f32 v[42:43], v[42:43], v[10:11]
	v_mfma_f32_32x32x16_bf16 v[16:31], v[56:59], v[84:87], v[16:31]
	global_load_dwordx4 v[56:59], v[174:175], off offset:96
	global_load_dwordx4 v[60:63], v[174:175], off offset:64
	global_load_dwordx4 v[72:75], v[236:237], off offset:-4096
	global_load_dwordx4 v[76:79], v[176:177], off offset:-4096
	s_waitcnt vmcnt(10)
	v_pk_mul_f32 v[46:47], v[118:119], v[14:15]
	v_pk_mul_f32 v[44:45], v[116:117], v[12:13]
	v_pk_mul_f32 v[40:41], v[40:41], v[8:9]
	s_waitcnt vmcnt(9)
	v_pk_mul_f32 v[38:39], v[66:67], v[6:7]
	v_pk_mul_f32 v[36:37], v[64:65], v[4:5]
	v_mfma_f32_32x32x16_bf16 v[16:31], v[96:99], v[100:103], v[16:31]
	global_load_dwordx4 v[96:99], v[168:169], off
	global_load_dwordx4 v[128:131], v[236:237], off offset:-3072
	s_waitcnt vmcnt(9)
	v_mul_f32_e64 v34, v82, v2
	v_mul_f32_e64 v35, v83, v3
	v_pk_mul_f32 v[32:33], v[80:81], v[0:1]
	s_nop 1
	v_mfma_f32_32x32x16_bf16 v[32:47], v[68:71], v[84:87], v[32:47]
	v_mfma_f32_32x32x16_bf16 v[16:31], v[104:107], v[108:111], v[16:31]
	global_load_dwordx4 v[104:107], v[168:169], off offset:1024
	global_load_dwordx4 v[132:135], v[236:237], off offset:-2048
	global_load_dwordx4 v[136:139], v[236:237], off offset:-1024
	global_load_dwordx4 v[140:143], v[236:237], off
	global_load_dwordx4 v[144:147], v[168:169], off offset:3072
	global_load_dwordx4 v[148:151], v[168:169], off offset:2048
	v_lshl_add_u64 v[168:169], v[168:169], 0, s[20:21]
	global_load_dwordx4 v[64:67], v[174:175], off offset:192
	global_load_dwordx4 v[116:119], v[174:175], off offset:224
	global_load_dwordx4 v[68:71], v[174:175], off offset:160
	global_load_dwordx4 v[80:83], v[174:175], off offset:128
	global_load_dwordx4 v[84:87], v[236:237], off offset:1024
	s_waitcnt vmcnt(19)
	v_mfma_f32_32x32x16_bf16 v[32:47], v[88:91], v[100:103], v[32:47]
	s_waitcnt vmcnt(18)
	v_mfma_f32_32x32x16_bf16 v[32:47], v[52:55], v[108:111], v[32:47]
	global_load_dwordx4 v[52:55], v[236:237], off offset:2048
	v_mfma_f32_32x32x16_bf16 v[16:31], v[120:123], v[112:115], v[16:31]
	s_waitcnt vmcnt(18)
	v_mfma_f32_32x32x16_bf16 v[32:47], v[92:95], v[112:115], v[32:47]
	s_nop 9
	v_mul_f32_e64 v6, v126, v22
	v_mul_f32_e64 v7, v127, v23
	v_mul_f32_e64 v4, v124, v20
	v_mul_f32_e64 v5, v125, v21
	v_add_co_u32_e32 v124, vcc, s14, v170
	s_mov_b32 s14, 0xa000
	s_nop 0
	v_addc_co_u32_e32 v125, vcc, 0, v171, vcc
	v_add_co_u32_e32 v126, vcc, s14, v170
	s_mov_b32 s14, 0xb000
	s_nop 0
	v_addc_co_u32_e32 v127, vcc, 0, v171, vcc
	s_waitcnt vmcnt(17)
	v_pk_mul_f32 v[14:15], v[58:59], v[30:31]
	v_pk_mul_f32 v[12:13], v[56:57], v[28:29]
	global_load_dwordx4 v[56:59], v[176:177], off
	s_waitcnt vmcnt(17)
	v_pk_mul_f32 v[10:11], v[62:63], v[26:27]
	v_pk_mul_f32 v[8:9], v[60:61], v[24:25]
	s_waitcnt vmcnt(15)
	v_pk_mul_f32 v[2:3], v[78:79], v[18:19]
	v_pk_mul_f32 v[0:1], v[76:77], v[16:17]
	s_waitcnt vmcnt(6)
	v_pk_mul_f32 v[26:27], v[66:67], v[42:43]
	v_mfma_f32_32x32x16_bf16 v[0:15], v[72:75], v[96:99], v[0:15]
	global_load_dwordx4 v[60:63], v[236:237], off offset:3072
	global_load_dwordx4 v[72:75], v[176:177], off offset:96
	global_load_dwordx4 v[76:79], v[176:177], off offset:32
	global_load_dwordx4 v[88:91], v[176:177], off offset:64
	s_waitcnt vmcnt(9)
	v_pk_mul_f32 v[30:31], v[118:119], v[46:47]
	v_pk_mul_f32 v[28:29], v[116:117], v[44:45]
	v_pk_mul_f32 v[24:25], v[64:65], v[40:41]
	s_waitcnt vmcnt(8)
	v_pk_mul_f32 v[22:23], v[70:71], v[38:39]
	v_pk_mul_f32 v[20:21], v[68:69], v[36:37]
	s_waitcnt vmcnt(7)
	v_pk_mul_f32 v[18:19], v[82:83], v[34:35]
	v_pk_mul_f32 v[16:17], v[80:81], v[32:33]
	global_load_dwordx4 v[92:95], v[238:239], off offset:-4096
	global_load_dwordx4 v[100:103], v[168:169], off
	v_mfma_f32_32x32x16_bf16 v[16:31], v[140:143], v[96:99], v[16:31]
	global_load_dwordx4 v[108:111], v[238:239], off offset:-3072
	global_load_dwordx4 v[112:115], v[168:169], off offset:1024
	global_load_dwordx4 v[120:123], v[238:239], off offset:-2048
	global_load_dwordx4 v[32:35], v[168:169], off offset:2048
	global_load_dwordx4 v[36:39], v[238:239], off offset:-1024
	global_load_dwordx4 v[40:43], v[168:169], off offset:3072
	v_lshl_add_u64 v[168:169], v[168:169], 0, s[20:21]
	global_load_dwordx4 v[44:47], v[176:177], off offset:224
	global_load_dwordx4 v[64:67], v[176:177], off offset:192
	global_load_dwordx4 v[68:71], v[176:177], off offset:160
	global_load_dwordx4 v[80:83], v[238:239], off
	s_waitcnt vmcnt(18)
	v_mfma_f32_32x32x16_bf16 v[16:31], v[84:87], v[104:107], v[16:31]
	v_mfma_f32_32x32x16_bf16 v[0:15], v[128:131], v[104:107], v[0:15]
	s_waitcnt vmcnt(17)
	v_mfma_f32_32x32x16_bf16 v[16:31], v[52:55], v[148:151], v[16:31]
	global_load_dwordx4 v[52:55], v[176:177], off offset:128
	global_load_dwordx4 v[84:87], v[238:239], off offset:1024
	v_mfma_f32_32x32x16_bf16 v[0:15], v[132:135], v[148:151], v[0:15]
	v_mfma_f32_32x32x16_bf16 v[0:15], v[136:139], v[144:147], v[0:15]
	s_waitcnt vmcnt(17)
	v_mfma_f32_32x32x16_bf16 v[16:31], v[60:63], v[144:147], v[16:31]
	s_waitcnt vmcnt(16)
	s_nop 8
	v_mul_f32_e64 v14, v74, v14
	v_mul_f32_e64 v15, v75, v15
	v_mul_f32_e64 v12, v72, v12
	v_mul_f32_e64 v13, v73, v13
	v_pk_mul_f32 v[2:3], v[58:59], v[2:3]
	v_pk_mul_f32 v[0:1], v[56:57], v[0:1]
	global_load_dwordx4 v[56:59], v[238:239], off offset:2048
	global_load_dwordx4 v[60:63], v[238:239], off offset:3072
	global_load_dwordx4 v[72:75], v[240:241], off offset:-4096
	s_waitcnt vmcnt(17)
	v_pk_mul_f32 v[10:11], v[90:91], v[10:11]
	v_pk_mul_f32 v[8:9], v[88:89], v[8:9]
	v_pk_mul_f32 v[6:7], v[78:79], v[6:7]
	v_pk_mul_f32 v[4:5], v[76:77], v[4:5]
	s_waitcnt vmcnt(8)
	v_pk_mul_f32 v[30:31], v[46:47], v[30:31]
	v_mfma_f32_32x32x16_bf16 v[0:15], v[92:95], v[100:103], v[0:15]
	v_mul_f32_e64 v28, v44, v28
	v_mul_f32_e64 v29, v45, v29
	s_waitcnt vmcnt(7)
	v_mul_f32_e64 v26, v66, v26
	v_mul_f32_e64 v27, v67, v27
	v_pk_mul_f32 v[24:25], v[64:65], v[24:25]
	s_waitcnt vmcnt(6)
	v_pk_mul_f32 v[22:23], v[70:71], v[22:23]
	v_pk_mul_f32 v[20:21], v[68:69], v[20:21]
	global_load_dwordx4 v[76:79], v[124:125], off offset:96
	global_load_dwordx4 v[88:91], v[124:125], off offset:32
	global_load_dwordx4 v[92:95], v[124:125], off offset:64
	global_load_dwordx4 v[96:99], v[126:127], off offset:-4096
	v_mfma_f32_32x32x16_bf16 v[0:15], v[108:111], v[112:115], v[0:15]
	s_waitcnt vmcnt(8)
	v_mul_f32_e64 v18, v54, v18
	v_mul_f32_e64 v19, v55, v19
	v_mul_f32_e64 v16, v52, v16
	v_mul_f32_e64 v17, v53, v17
	v_mfma_f32_32x32x16_bf16 v[0:15], v[120:123], v[32:35], v[0:15]
	global_load_dwordx4 v[104:107], v[168:169], off
	global_load_dwordx4 v[108:111], v[240:241], off offset:-3072
	global_load_dwordx4 v[116:119], v[168:169], off offset:1024
	global_load_dwordx4 v[120:123], v[240:241], off offset:-2048
	v_mfma_f32_32x32x16_bf16 v[16:31], v[80:83], v[100:103], v[16:31]
	s_waitcnt vmcnt(11)
	v_mfma_f32_32x32x16_bf16 v[16:31], v[84:87], v[112:115], v[16:31]
	v_mfma_f32_32x32x16_bf16 v[0:15], v[36:39], v[40:43], v[0:15]
	global_load_dwordx4 v[36:39], v[168:169], off offset:2048
	global_load_dwordx4 v[44:47], v[240:241], off offset:-1024
	global_load_dwordx4 v[52:55], v[168:169], off offset:3072
	v_lshl_add_u64 v[168:169], v[168:169], 0, s[20:21]
	global_load_dwordx4 v[64:67], v[124:125], off offset:224
	global_load_dwordx4 v[68:71], v[124:125], off offset:192
	global_load_dwordx4 v[80:83], v[124:125], off offset:160
	global_load_dwordx4 v[84:87], v[240:241], off
	s_waitcnt vmcnt(14)
	s_nop 3
	v_pk_mul_f32 v[14:15], v[78:79], v[14:15]
	v_mfma_f32_32x32x16_bf16 v[16:31], v[56:59], v[32:35], v[16:31]
	global_load_dwordx4 v[32:35], v[124:125], off offset:128
	global_load_dwordx4 v[56:59], v[240:241], off offset:1024
	v_mul_f32_e64 v12, v76, v12
	v_mul_f32_e64 v13, v77, v13
	s_waitcnt vmcnt(14)
	v_pk_mul_f32 v[10:11], v[94:95], v[10:11]
	v_pk_mul_f32 v[8:9], v[92:93], v[8:9]
	v_pk_mul_f32 v[6:7], v[90:91], v[6:7]
	v_pk_mul_f32 v[4:5], v[88:89], v[4:5]
	s_waitcnt vmcnt(13)
	v_pk_mul_f32 v[2:3], v[98:99], v[2:3]
	v_mfma_f32_32x32x16_bf16 v[16:31], v[60:63], v[40:43], v[16:31]
	global_load_dwordx4 v[40:43], v[240:241], off offset:2048
	global_load_dwordx4 v[60:63], v[240:241], off offset:3072
	v_mul_f32_e64 v0, v96, v0
	v_mul_f32_e64 v1, v97, v1
	s_waitcnt vmcnt(14)
	s_nop 0
	v_mfma_f32_32x32x16_bf16 v[0:15], v[72:75], v[104:107], v[0:15]
	global_load_dwordx4 v[72:75], v[126:127], off offset:96
	global_load_dwordx4 v[76:79], v[126:127], off offset:64
	global_load_dwordx4 v[88:91], v[244:245], off offset:-4096
	global_load_dwordx4 v[92:95], v[126:127], off offset:32
	global_load_dwordx4 v[96:99], v[126:127], off
	s_waitcnt vmcnt(12)
	v_pk_mul_f32 v[30:31], v[66:67], v[30:31]
	v_pk_mul_f32 v[28:29], v[64:65], v[28:29]
	s_waitcnt vmcnt(11)
	v_pk_mul_f32 v[26:27], v[70:71], v[26:27]
	v_pk_mul_f32 v[24:25], v[68:69], v[24:25]
	s_waitcnt vmcnt(10)
	v_pk_mul_f32 v[22:23], v[82:83], v[22:23]
	v_pk_mul_f32 v[20:21], v[80:81], v[20:21]
	v_mfma_f32_32x32x16_bf16 v[0:15], v[108:111], v[116:119], v[0:15]
	global_load_dwordx4 v[100:103], v[168:169], off
	global_load_dwordx4 v[108:111], v[168:169], off offset:1024
	global_load_dwordx4 v[112:115], v[244:245], off offset:-3072
	s_waitcnt vmcnt(11)
	v_mul_f32_e64 v18, v34, v18
	v_mul_f32_e64 v19, v35, v19
	v_pk_mul_f32 v[16:17], v[32:33], v[16:17]
	v_mfma_f32_32x32x16_bf16 v[0:15], v[120:123], v[36:39], v[0:15]
	v_add_co_u32_e32 v120, vcc, s14, v170
	s_mov_b32 s14, 0xc000
	s_nop 0
	v_addc_co_u32_e32 v121, vcc, 0, v171, vcc
	v_add_co_u32_e32 v124, vcc, s14, v170
	v_mfma_f32_32x32x16_bf16 v[16:31], v[84:87], v[104:107], v[16:31]
	s_nop 0
	v_addc_co_u32_e32 v125, vcc, 0, v171, vcc
	s_mov_b32 s14, 0xd000
	s_waitcnt vmcnt(10)
	v_mfma_f32_32x32x16_bf16 v[16:31], v[56:59], v[116:119], v[16:31]
	v_mfma_f32_32x32x16_bf16 v[0:15], v[44:47], v[52:55], v[0:15]
	global_load_dwordx4 v[44:47], v[120:121], off offset:32
	global_load_dwordx4 v[32:35], v[244:245], off offset:-2048
	global_load_dwordx4 v[64:67], v[168:169], off offset:2048
	global_load_dwordx4 v[56:59], v[244:245], off offset:-1024
	global_load_dwordx4 v[68:71], v[168:169], off offset:3072
	v_lshl_add_u64 v[168:169], v[168:169], 0, s[20:21]
	global_load_dwordx4 v[80:83], v[126:127], off offset:224
	global_load_dwordx4 v[84:87], v[126:127], off offset:192
	global_load_dwordx4 v[104:107], v[244:245], off
	s_waitcnt vmcnt(15)
	s_nop 2
	v_pk_mul_f32 v[14:15], v[74:75], v[14:15]
	v_mfma_f32_32x32x16_bf16 v[16:31], v[40:43], v[36:39], v[16:31]
	global_load_dwordx4 v[36:39], v[126:127], off offset:160
	global_load_dwordx4 v[40:43], v[126:127], off offset:128
	global_load_dwordx4 v[116:119], v[244:245], off offset:1024
	v_mul_f32_e64 v12, v72, v12
	v_mul_f32_e64 v13, v73, v13
	s_waitcnt vmcnt(17)
	v_pk_mul_f32 v[10:11], v[78:79], v[10:11]
	v_pk_mul_f32 v[8:9], v[76:77], v[8:9]
	s_waitcnt vmcnt(15)
	v_pk_mul_f32 v[6:7], v[94:95], v[6:7]
	v_pk_mul_f32 v[4:5], v[92:93], v[4:5]
	s_waitcnt vmcnt(14)
	v_pk_mul_f32 v[2:3], v[98:99], v[2:3]
	v_mfma_f32_32x32x16_bf16 v[16:31], v[60:63], v[52:55], v[16:31]
	global_load_dwordx4 v[52:55], v[244:245], off offset:2048
	global_load_dwordx4 v[60:63], v[244:245], off offset:3072
	v_mul_f32_e64 v0, v96, v0
	v_mul_f32_e64 v1, v97, v1
	s_waitcnt vmcnt(15)
	s_nop 0
	v_mfma_f32_32x32x16_bf16 v[0:15], v[88:91], v[100:103], v[0:15]
	global_load_dwordx4 v[72:75], v[120:121], off offset:96
	global_load_dwordx4 v[76:79], v[120:121], off offset:64
	global_load_dwordx4 v[88:91], v[246:247], off offset:-4096
	global_load_dwordx4 v[92:95], v[124:125], off offset:-4096
	s_waitcnt vmcnt(11)
	v_pk_mul_f32 v[30:31], v[82:83], v[30:31]
	v_mfma_f32_32x32x16_bf16 v[0:15], v[112:115], v[108:111], v[0:15]
	v_mul_f32_e64 v28, v80, v28
	v_mul_f32_e64 v29, v81, v29
	s_waitcnt vmcnt(10)
	v_mul_f32_e64 v26, v86, v26
	v_mul_f32_e64 v27, v87, v27
	v_pk_mul_f32 v[24:25], v[84:85], v[24:25]
	s_waitcnt vmcnt(8)
	v_pk_mul_f32 v[22:23], v[38:39], v[22:23]
	v_pk_mul_f32 v[20:21], v[36:37], v[20:21]
	s_waitcnt vmcnt(7)
	v_pk_mul_f32 v[18:19], v[42:43], v[18:19]
	v_pk_mul_f32 v[16:17], v[40:41], v[16:17]
	v_mfma_f32_32x32x16_bf16 v[0:15], v[32:35], v[64:67], v[0:15]
	global_load_dwordx4 v[32:35], v[168:169], off
	global_load_dwordx4 v[96:99], v[246:247], off offset:-3072
	global_load_dwordx4 v[112:115], v[168:169], off offset:1024
	global_load_dwordx4 v[36:39], v[246:247], off offset:-2048
	global_load_dwordx4 v[40:43], v[168:169], off offset:2048
	v_mfma_f32_32x32x16_bf16 v[16:31], v[104:107], v[100:103], v[16:31]
	s_waitcnt vmcnt(11)
	v_mfma_f32_32x32x16_bf16 v[16:31], v[116:119], v[108:111], v[16:31]
	v_mfma_f32_32x32x16_bf16 v[0:15], v[56:59], v[68:71], v[0:15]
	global_load_dwordx4 v[56:59], v[246:247], off offset:-1024
	global_load_dwordx4 v[80:83], v[120:121], off offset:224
	global_load_dwordx4 v[84:87], v[168:169], off offset:3072
	v_lshl_add_u64 v[168:169], v[168:169], 0, s[20:21]
	global_load_dwordx4 v[100:103], v[120:121], off offset:192
	global_load_dwordx4 v[104:107], v[246:247], off
	global_load_dwordx4 v[108:111], v[120:121], off offset:160
	s_nop 5
	v_pk_mul_f32 v[6:7], v[46:47], v[6:7]
	s_waitcnt vmcnt(16)
	v_mfma_f32_32x32x16_bf16 v[16:31], v[52:55], v[64:67], v[16:31]
	global_load_dwordx4 v[52:55], v[120:121], off offset:128
	global_load_dwordx4 v[64:67], v[246:247], off offset:1024
	v_mul_f32_e64 v4, v44, v4
	v_mul_f32_e64 v5, v45, v5
	global_load_dwordx4 v[44:47], v[124:125], off
	s_waitcnt vmcnt(17)
	v_pk_mul_f32 v[14:15], v[74:75], v[14:15]
	v_pk_mul_f32 v[12:13], v[72:73], v[12:13]
	s_waitcnt vmcnt(16)
	v_pk_mul_f32 v[10:11], v[78:79], v[10:11]
	v_pk_mul_f32 v[8:9], v[76:77], v[8:9]
	v_mfma_f32_32x32x16_bf16 v[16:31], v[60:63], v[68:71], v[16:31]
	global_load_dwordx4 v[60:63], v[246:247], off offset:2048
	global_load_dwordx4 v[68:71], v[246:247], off offset:3072
	s_waitcnt vmcnt(16)
	v_mul_f32_e64 v2, v94, v2
	v_mul_f32_e64 v3, v95, v3
	v_pk_mul_f32 v[0:1], v[92:93], v[0:1]
	s_waitcnt vmcnt(15)
	s_nop 0
	v_mfma_f32_32x32x16_bf16 v[0:15], v[88:91], v[32:35], v[0:15]
	global_load_dwordx4 v[72:75], v[124:125], off offset:96
	global_load_dwordx4 v[76:79], v[124:125], off offset:64
	global_load_dwordx4 v[88:91], v[124:125], off offset:32
	global_load_dwordx4 v[92:95], v[248:249], off offset:-4096
	s_waitcnt vmcnt(13)
	v_pk_mul_f32 v[30:31], v[82:83], v[30:31]
	v_mfma_f32_32x32x16_bf16 v[0:15], v[96:99], v[112:115], v[0:15]
	v_mul_f32_e64 v28, v80, v28
	v_mul_f32_e64 v29, v81, v29
	s_waitcnt vmcnt(11)
	v_mul_f32_e64 v26, v102, v26
	v_mul_f32_e64 v27, v103, v27
	v_pk_mul_f32 v[24:25], v[100:101], v[24:25]
	s_waitcnt vmcnt(9)
	v_pk_mul_f32 v[22:23], v[110:111], v[22:23]
	v_pk_mul_f32 v[20:21], v[108:109], v[20:21]
	s_waitcnt vmcnt(8)
	v_pk_mul_f32 v[18:19], v[54:55], v[18:19]
	v_pk_mul_f32 v[16:17], v[52:53], v[16:17]
	v_mfma_f32_32x32x16_bf16 v[0:15], v[36:39], v[40:43], v[0:15]
	global_load_dwordx4 v[36:39], v[168:169], off
	global_load_dwordx4 v[96:99], v[168:169], off offset:1024
	global_load_dwordx4 v[116:119], v[248:249], off offset:-3072
	global_load_dwordx4 v[120:123], v[248:249], off offset:-2048
	v_mfma_f32_32x32x16_bf16 v[16:31], v[104:107], v[32:35], v[16:31]
	global_load_dwordx4 v[32:35], v[168:169], off offset:2048
	s_waitcnt vmcnt(12)
	v_mfma_f32_32x32x16_bf16 v[16:31], v[64:67], v[112:115], v[16:31]
	v_mfma_f32_32x32x16_bf16 v[0:15], v[56:59], v[84:87], v[0:15]
	global_load_dwordx4 v[52:55], v[248:249], off offset:-1024
	global_load_dwordx4 v[56:59], v[124:125], off offset:224
	global_load_dwordx4 v[64:67], v[168:169], off offset:3072
	v_lshl_add_u64 v[168:169], v[168:169], 0, s[20:21]
	global_load_dwordx4 v[80:83], v[124:125], off offset:192
	global_load_dwordx4 v[100:103], v[124:125], off offset:160
	global_load_dwordx4 v[104:107], v[248:249], off
	s_waitcnt vmcnt(17)
	s_nop 4
	v_pk_mul_f32 v[2:3], v[46:47], v[2:3]
	s_waitcnt vmcnt(16)
	v_mfma_f32_32x32x16_bf16 v[16:31], v[60:63], v[40:43], v[16:31]
	global_load_dwordx4 v[40:43], v[124:125], off offset:128
	global_load_dwordx4 v[60:63], v[248:249], off offset:1024
	global_load_dwordx4 v[108:111], v[248:249], off offset:2048
	v_mul_f32_e64 v0, v44, v0
	v_mul_f32_e64 v1, v45, v1
	v_add_co_u32_e32 v124, vcc, s14, v170
	s_mov_b32 s14, 0xe000
	s_nop 0
	v_addc_co_u32_e32 v125, vcc, 0, v171, vcc
	s_waitcnt vmcnt(18)
	v_mfma_f32_32x32x16_bf16 v[16:31], v[68:71], v[84:87], v[16:31]
	global_load_dwordx4 v[44:47], v[248:249], off offset:3072
	global_load_dwordx4 v[68:71], v[250:251], off offset:-4096
	s_waitcnt vmcnt(19)
	v_mul_f32_e64 v14, v74, v14
	v_mul_f32_e64 v15, v75, v15
	v_pk_mul_f32 v[12:13], v[72:73], v[12:13]
	s_waitcnt vmcnt(18)
	v_pk_mul_f32 v[10:11], v[78:79], v[10:11]
	v_pk_mul_f32 v[8:9], v[76:77], v[8:9]
	s_waitcnt vmcnt(17)
	v_pk_mul_f32 v[6:7], v[90:91], v[6:7]
	v_pk_mul_f32 v[4:5], v[88:89], v[4:5]
	v_add_co_u32_e32 v126, vcc, s14, v170
	s_waitcnt vmcnt(15)
	v_mfma_f32_32x32x16_bf16 v[0:15], v[92:95], v[36:39], v[0:15]
	v_addc_co_u32_e32 v127, vcc, 0, v171, vcc
	global_load_dwordx4 v[72:75], v[124:125], off offset:96
	global_load_dwordx4 v[76:79], v[124:125], off offset:32
	global_load_dwordx4 v[84:87], v[124:125], off offset:64
	global_load_dwordx4 v[88:91], v[126:127], off offset:-4096
	s_or_b32 s14, s1, s0
	s_ashr_i32 s15, s14, 31
	s_waitcnt vmcnt(17)
	v_mfma_f32_32x32x16_bf16 v[0:15], v[116:119], v[96:99], v[0:15]
	global_load_dwordx4 v[92:95], v[168:169], off
	global_load_dwordx4 v[112:115], v[250:251], off offset:-3072
	global_load_dwordx4 v[116:119], v[168:169], off offset:1024
	s_lshl_b64 s[14:15], s[14:15], 15
	s_cmp_lg_u32 s0, 0
	s_waitcnt vmcnt(16)
	v_pk_mul_f32 v[30:31], v[58:59], v[30:31]
	v_pk_mul_f32 v[28:29], v[56:57], v[28:29]
	s_waitcnt vmcnt(14)
	v_pk_mul_f32 v[26:27], v[82:83], v[26:27]
	v_pk_mul_f32 v[24:25], v[80:81], v[24:25]
	s_waitcnt vmcnt(13)
	v_pk_mul_f32 v[22:23], v[102:103], v[22:23]
	v_pk_mul_f32 v[20:21], v[100:101], v[20:21]
	v_mfma_f32_32x32x16_bf16 v[0:15], v[120:123], v[32:35], v[0:15]
	s_waitcnt vmcnt(11)
	v_mul_f32_e64 v18, v42, v18
	v_mul_f32_e64 v19, v43, v19
	v_mul_f32_e64 v16, v40, v16
	v_mul_f32_e64 v17, v41, v17
	v_mfma_f32_32x32x16_bf16 v[0:15], v[52:55], v[64:67], v[0:15]
	s_nop 0
	v_mfma_f32_32x32x16_bf16 v[16:31], v[104:107], v[36:39], v[16:31]
	global_load_dwordx4 v[36:39], v[250:251], off offset:-2048
	global_load_dwordx4 v[40:43], v[168:169], off offset:2048
	global_load_dwordx4 v[52:55], v[250:251], off offset:-1024
	s_waitcnt vmcnt(9)
	s_nop 5
	v_mul_f32_e64 v14, v74, v14
	v_mul_f32_e64 v15, v75, v15
	v_mfma_f32_32x32x16_bf16 v[16:31], v[60:63], v[96:99], v[16:31]
	global_load_dwordx4 v[56:59], v[124:125], off offset:224
	global_load_dwordx4 v[60:63], v[168:169], off offset:3072
	v_lshl_add_u64 v[168:169], v[168:169], 0, s[20:21]
	global_load_dwordx4 v[80:83], v[124:125], off offset:192
	global_load_dwordx4 v[96:99], v[124:125], off offset:160
	global_load_dwordx4 v[100:103], v[250:251], off
	v_pk_mul_f32 v[12:13], v[72:73], v[12:13]
	s_waitcnt vmcnt(12)
	v_pk_mul_f32 v[10:11], v[86:87], v[10:11]
	v_pk_mul_f32 v[8:9], v[84:85], v[8:9]
	v_pk_mul_f32 v[6:7], v[78:79], v[6:7]
	v_pk_mul_f32 v[4:5], v[76:77], v[4:5]
	s_waitcnt vmcnt(11)
	v_pk_mul_f32 v[2:3], v[90:91], v[2:3]
	v_mfma_f32_32x32x16_bf16 v[16:31], v[108:111], v[32:35], v[16:31]
	global_load_dwordx4 v[32:35], v[124:125], off offset:128
	global_load_dwordx4 v[104:107], v[250:251], off offset:1024
	v_mul_f32_e64 v0, v88, v0
	v_mul_f32_e64 v1, v89, v1
	v_mfma_f32_32x32x16_bf16 v[16:31], v[44:47], v[64:67], v[16:31]
	global_load_dwordx4 v[44:47], v[250:251], off offset:2048
	global_load_dwordx4 v[64:67], v[250:251], off offset:3072
	s_waitcnt vmcnt(14)
	v_mfma_f32_32x32x16_bf16 v[0:15], v[68:71], v[92:95], v[0:15]
	global_load_dwordx4 v[68:71], v[126:127], off offset:96
	global_load_dwordx4 v[72:75], v[126:127], off offset:64
	global_load_dwordx4 v[76:79], v[252:253], off offset:-4096
	global_load_dwordx4 v[84:87], v[126:127], off offset:32
	global_load_dwordx4 v[88:91], v[126:127], off
	s_waitcnt vmcnt(13)
	s_nop 1
	v_pk_mul_f32 v[30:31], v[58:59], v[30:31]
	v_mfma_f32_32x32x16_bf16 v[0:15], v[112:115], v[116:119], v[0:15]
	v_mul_f32_e64 v28, v56, v28
	v_mul_f32_e64 v29, v57, v29
	s_waitcnt vmcnt(11)
	v_mul_f32_e64 v26, v82, v26
	v_mul_f32_e64 v27, v83, v27
	v_pk_mul_f32 v[24:25], v[80:81], v[24:25]
	s_waitcnt vmcnt(10)
	v_pk_mul_f32 v[22:23], v[98:99], v[22:23]
	v_pk_mul_f32 v[20:21], v[96:97], v[20:21]
	s_waitcnt vmcnt(8)
	v_pk_mul_f32 v[18:19], v[34:35], v[18:19]
	v_pk_mul_f32 v[16:17], v[32:33], v[16:17]
	v_mfma_f32_32x32x16_bf16 v[0:15], v[36:39], v[40:43], v[0:15]
	global_load_dwordx4 v[36:39], v[168:169], off
	global_load_dwordx4 v[108:111], v[252:253], off offset:-3072
	global_load_dwordx4 v[112:115], v[168:169], off offset:1024
	global_load_dwordx4 v[120:123], v[172:173], off
	global_load_dwordx4 v[32:35], v[168:169], off offset:2048
	v_mfma_f32_32x32x16_bf16 v[16:31], v[100:103], v[92:95], v[16:31]
	s_waitcnt vmcnt(12)
	v_mfma_f32_32x32x16_bf16 v[16:31], v[104:107], v[116:119], v[16:31]
	v_mfma_f32_32x32x16_bf16 v[0:15], v[52:55], v[60:63], v[0:15]
	global_load_dwordx4 v[52:55], v[252:253], off offset:-2048
	global_load_dwordx4 v[56:59], v[252:253], off offset:-1024
	global_load_dwordx4 v[80:83], v[126:127], off offset:224
	global_load_dwordx4 v[92:95], v[168:169], off offset:3072
	global_load_dwordx4 v[96:99], v[126:127], off offset:192
	global_load_dwordx4 v[100:103], v[126:127], off offset:160
	global_load_dwordx4 v[104:107], v[252:253], off
	s_waitcnt vmcnt(16)
	s_nop 3
	v_pk_mul_f32 v[14:15], v[14:15], v[70:71]
	v_mfma_f32_32x32x16_bf16 v[16:31], v[44:47], v[40:43], v[16:31]
	global_load_dwordx4 v[40:43], v[126:127], off offset:128
	v_mul_f32_e64 v12, v12, v68
	v_mul_f32_e64 v13, v13, v69
	s_waitcnt vmcnt(16)
	v_mul_f32_e64 v10, v10, v74
	v_mul_f32_e64 v11, v11, v75
	v_pk_mul_f32 v[8:9], v[8:9], v[72:73]
	s_waitcnt vmcnt(14)
	v_pk_mul_f32 v[6:7], v[6:7], v[86:87]
	v_pk_mul_f32 v[4:5], v[4:5], v[84:85]
	s_waitcnt vmcnt(13)
	v_pk_mul_f32 v[2:3], v[2:3], v[90:91]
	v_mfma_f32_32x32x16_bf16 v[16:31], v[64:67], v[60:63], v[16:31]
	global_load_dwordx4 v[44:47], v[252:253], off offset:1024
	global_load_dwordx4 v[60:63], v[172:173], off offset:32
	v_mul_f32_e64 v0, v0, v88
	v_mul_f32_e64 v1, v1, v89
	global_load_dwordx4 v[64:67], v[252:253], off offset:2048
	global_load_dwordx4 v[68:71], v[172:173], off offset:64
	global_load_dwordx4 v[72:75], v[252:253], off offset:3072
	s_waitcnt vmcnt(10)
	s_nop 3
	v_pk_mul_f32 v[30:31], v[30:31], v[82:83]
	v_mfma_f32_32x32x16_bf16 v[0:15], v[76:79], v[36:39], v[0:15]
	v_mul_f32_e64 v28, v28, v80
	v_mul_f32_e64 v29, v29, v81
	s_waitcnt vmcnt(8)
	v_mul_f32_e64 v26, v26, v98
	v_mul_f32_e64 v27, v27, v99
	v_pk_mul_f32 v[24:25], v[24:25], v[96:97]
	s_waitcnt vmcnt(7)
	v_pk_mul_f32 v[22:23], v[22:23], v[102:103]
	v_pk_mul_f32 v[20:21], v[20:21], v[100:101]
	s_waitcnt vmcnt(5)
	v_pk_mul_f32 v[18:19], v[18:19], v[42:43]
	v_mfma_f32_32x32x16_bf16 v[0:15], v[108:111], v[112:115], v[0:15]
	v_mul_f32_e64 v16, v16, v40
	v_mul_f32_e64 v17, v17, v41
	v_mfma_f32_32x32x16_bf16 v[0:15], v[52:55], v[32:35], v[0:15]
	global_load_dwordx4 v[52:55], v[172:173], off offset:96
	global_load_dwordx4 v[76:79], v[172:173], off offset:128
	global_load_dwordx4 v[84:87], v[172:173], off offset:160
	v_mfma_f32_32x32x16_bf16 v[16:31], v[104:107], v[36:39], v[16:31]
	global_load_dwordx4 v[36:39], v[172:173], off offset:192
	s_waitcnt vmcnt(8)
	v_mfma_f32_32x32x16_bf16 v[16:31], v[44:47], v[112:115], v[16:31]
	s_waitcnt vmcnt(6)
	v_mfma_f32_32x32x16_bf16 v[16:31], v[64:67], v[32:35], v[16:31]
	v_mfma_f32_32x32x16_bf16 v[0:15], v[56:59], v[92:95], v[0:15]
	s_waitcnt vmcnt(4)
	v_mfma_f32_32x32x16_bf16 v[16:31], v[72:75], v[92:95], v[16:31]
	s_nop 9
	v_mul_f32_e32 v40, v120, v0
	v_mul_f32_e32 v41, v121, v1
	v_lshl_add_u64 v[0:1], v[156:157], 0, s[14:15]
	v_mul_f32_e32 v2, v122, v2
	v_mul_f32_e32 v3, v123, v3
	v_mul_f32_e32 v4, v60, v4
	v_mul_f32_e32 v5, v61, v5
	v_mul_f32_e32 v6, v62, v6
	v_mul_f32_e32 v7, v63, v7
	v_mul_f32_e32 v8, v68, v8
	v_mul_f32_e32 v9, v69, v9
	v_mul_f32_e32 v10, v70, v10
	v_mul_f32_e32 v11, v71, v11
	v_mul_f32_e32 v31, v51, v31
	v_mul_f32_e32 v28, v48, v28
	v_mul_f32_e32 v29, v49, v29
	v_mul_f32_e32 v30, v50, v30
	s_waitcnt vmcnt(3)
	v_mul_f32_e32 v12, v52, v12
	v_mul_f32_e32 v13, v53, v13
	v_mul_f32_e32 v14, v54, v14
	v_mul_f32_e32 v15, v55, v15
	global_store_dword v[0:1], v40, off
	global_store_dword v[0:1], v41, off offset:256
	global_store_dword v[0:1], v2, off offset:512
	global_store_dword v[0:1], v3, off offset:768
	global_store_dword v[0:1], v4, off offset:1024
	global_store_dword v[0:1], v5, off offset:1280
	global_store_dword v[0:1], v6, off offset:1536
	global_store_dword v[0:1], v7, off offset:1792
	global_store_dword v[0:1], v8, off offset:2048
	global_store_dword v[0:1], v9, off offset:2304
	global_store_dword v[0:1], v10, off offset:2560
	global_store_dword v[0:1], v11, off offset:2816
	global_store_dword v[0:1], v12, off offset:3072
	global_store_dword v[0:1], v13, off offset:3328
	global_store_dword v[0:1], v14, off offset:3584
	global_store_dword v[0:1], v15, off offset:3840
	v_add_co_u32_e32 v0, vcc, s29, v0
	s_waitcnt vmcnt(18)
	v_mul_f32_e32 v16, v76, v16
	v_addc_co_u32_e32 v1, vcc, 0, v1, vcc
	v_mul_f32_e32 v17, v77, v17
	v_mul_f32_e32 v18, v78, v18
	v_mul_f32_e32 v19, v79, v19
	s_waitcnt vmcnt(17)
	v_mul_f32_e32 v20, v84, v20
	v_mul_f32_e32 v21, v85, v21
	v_mul_f32_e32 v22, v86, v22
	v_mul_f32_e32 v23, v87, v23
	s_waitcnt vmcnt(16)
	v_mul_f32_e32 v24, v36, v24
	v_mul_f32_e32 v25, v37, v25
	v_mul_f32_e32 v26, v38, v26
	v_mul_f32_e32 v27, v39, v27
	global_store_dword v[0:1], v16, off
	global_store_dword v[0:1], v17, off offset:256
	global_store_dword v[0:1], v18, off offset:512
	global_store_dword v[0:1], v19, off offset:768
	global_store_dword v[0:1], v20, off offset:1024
	global_store_dword v[0:1], v21, off offset:1280
	global_store_dword v[0:1], v22, off offset:1536
	global_store_dword v[0:1], v23, off offset:1792
	global_store_dword v[0:1], v24, off offset:2048
	global_store_dword v[0:1], v25, off offset:2304
	global_store_dword v[0:1], v26, off offset:2560
	global_store_dword v[0:1], v27, off offset:2816
	global_store_dword v[0:1], v28, off offset:3072
	global_store_dword v[0:1], v29, off offset:3328
	global_store_dword v[0:1], v30, off offset:3584
	global_store_dword v[0:1], v31, off offset:3840
	s_cbranch_scc1 .LBB0_209
	s_lshr_b32 s0, s6, 4
	s_and_b32 s0, s0, 3
	s_lshl_b32 s0, s0, 10
	s_add_u32 s0, s8, s0
	s_addc_u32 s1, s9, 0
	v_lshl_add_u64 v[0:1], v[158:159], 0, s[0:1]
	v_add_co_u32_e32 v4, vcc, 0x3d80000, v0
	s_nop 1
	v_addc_co_u32_e32 v5, vcc, 0, v1, vcc
	global_load_dword v40, v[4:5], off
	v_lshl_add_u64 v[4:5], v[4:5], 0, s[86:87]
	global_load_dword v41, v[4:5], off
	v_lshl_add_u64 v[4:5], v[4:5], 0, s[86:87]
	global_load_dword v42, v[4:5], off
	v_lshl_add_u64 v[4:5], v[4:5], 0, s[86:87]
	global_load_dword v43, v[4:5], off
	v_lshl_add_u64 v[4:5], v[4:5], 0, s[86:87]
	global_load_dword v44, v[4:5], off
	v_lshl_add_u64 v[4:5], v[4:5], 0, s[86:87]
	global_load_dword v45, v[4:5], off
	v_lshl_add_u64 v[4:5], v[4:5], 0, s[86:87]
	global_load_dword v46, v[4:5], off
	v_lshl_add_u64 v[4:5], v[4:5], 0, s[86:87]
	global_load_dword v47, v[4:5], off
	v_lshl_add_u64 v[4:5], v[4:5], 0, s[86:87]
	global_load_dword v48, v[4:5], off
	v_lshl_add_u64 v[4:5], v[4:5], 0, s[86:87]
	global_load_dword v49, v[4:5], off
	v_lshl_add_u64 v[4:5], v[4:5], 0, s[86:87]
	global_load_dword v50, v[4:5], off
	v_lshl_add_u64 v[4:5], v[4:5], 0, s[86:87]
	global_load_dword v51, v[4:5], off
	v_lshl_add_u64 v[4:5], v[4:5], 0, s[86:87]
	global_load_dword v52, v[4:5], off
	v_lshl_add_u64 v[4:5], v[4:5], 0, s[86:87]
	global_load_dword v53, v[4:5], off
	v_lshl_add_u64 v[4:5], v[4:5], 0, s[86:87]
	global_load_dword v54, v[4:5], off
	v_lshl_add_u64 v[4:5], v[4:5], 0, s[86:87]
	global_load_dword v55, v[4:5], off
	s_waitcnt vmcnt(15)
	v_mul_f32_e32 v2, 1.0, v40
	s_waitcnt vmcnt(14)
	v_mul_f32_e32 v2, v2, v41
	s_waitcnt vmcnt(13)
	v_mul_f32_e32 v2, v2, v42
	s_waitcnt vmcnt(12)
	v_mul_f32_e32 v2, v2, v43
	s_waitcnt vmcnt(11)
	v_mul_f32_e32 v2, v2, v44
	s_waitcnt vmcnt(10)
	v_mul_f32_e32 v2, v2, v45
	s_waitcnt vmcnt(9)
	v_mul_f32_e32 v2, v2, v46
	s_waitcnt vmcnt(8)
	v_mul_f32_e32 v2, v2, v47
	s_waitcnt vmcnt(7)
	v_mul_f32_e32 v2, v2, v48
	s_waitcnt vmcnt(6)
	v_mul_f32_e32 v2, v2, v49
	s_waitcnt vmcnt(5)
	v_mul_f32_e32 v2, v2, v50
	s_waitcnt vmcnt(4)
	v_mul_f32_e32 v2, v2, v51
	s_waitcnt vmcnt(3)
	v_mul_f32_e32 v2, v2, v52
	s_waitcnt vmcnt(2)
	v_mul_f32_e32 v2, v2, v53
	s_waitcnt vmcnt(1)
	v_mul_f32_e32 v2, v2, v54
	s_waitcnt vmcnt(0)
	v_mul_f32_e32 v2, v2, v55
	v_lshl_add_u32 v0, s7, 8, v152
	v_ashrrev_i32_e32 v1, 31, v0
	v_lshl_add_u64 v[0:1], v[0:1], 2, s[12:13]
	global_store_dword v[0:1], v2, off
	s_branch .LBB0_209

.LBB0_247:
	v_ashrrev_i32_e32 v7, 31, v6
	v_lshlrev_b64 v[10:11], 12, v[6:7]
	v_lshl_add_u64 v[22:23], v[0:1], 0, v[10:11]
	global_load_dwordx4 v[32:35], v[22:23], off
	global_load_dwordx4 v[36:39], v[22:23], off offset:64
	global_load_dwordx4 v[40:43], v[22:23], off offset:128
	global_load_dwordx4 v[44:47], v[22:23], off offset:192
	global_load_dwordx4 v[48:51], v[22:23], off offset:256
	global_load_dwordx4 v[52:55], v[22:23], off offset:320
	global_load_dwordx4 v[56:59], v[22:23], off offset:384
	global_load_dwordx4 v[60:63], v[22:23], off offset:448
	global_load_dwordx4 v[64:67], v[22:23], off offset:512
	global_load_dwordx4 v[68:71], v[22:23], off offset:576
	global_load_dwordx4 v[72:75], v[22:23], off offset:640
	global_load_dwordx4 v[76:79], v[22:23], off offset:704
	global_load_dwordx4 v[80:83], v[22:23], off offset:768
	global_load_dwordx4 v[84:87], v[22:23], off offset:832
	global_load_dwordx4 v[88:91], v[22:23], off offset:896
	global_load_dwordx4 v[92:95], v[22:23], off offset:960
	global_load_dwordx4 v[96:99], v[2:3], off
	global_load_dwordx4 v[100:103], v[2:3], off offset:64
	global_load_dwordx4 v[104:107], v[2:3], off offset:128
	global_load_dwordx4 v[108:111], v[2:3], off offset:192
	global_load_dwordx4 v[112:115], v[2:3], off offset:256
	global_load_dwordx4 v[116:119], v[2:3], off offset:320
	global_load_dwordx4 v[120:123], v[2:3], off offset:384
	global_load_dwordx4 v[124:127], v[2:3], off offset:448
	global_load_dwordx4 v[128:131], v[2:3], off offset:512
	global_load_dwordx4 v[132:135], v[2:3], off offset:576
	global_load_dwordx4 v[136:139], v[2:3], off offset:640
	global_load_dwordx4 v[140:143], v[2:3], off offset:704
	global_load_dwordx4 v[144:147], v[2:3], off offset:768
	global_load_dwordx4 v[148:151], v[2:3], off offset:832
	global_load_dwordx4 v[152:155], v[2:3], off offset:896
	global_load_dwordx4 v[156:159], v[2:3], off offset:960
	s_add_i32 s0, s0, s64
	v_add_u32_e32 v6, s47, v6
	s_cmpk_gt_i32 s0, 0x1ff
	s_waitcnt lgkmcnt(0)
	s_barrier
	s_waitcnt vmcnt(15)
	v_mfma_f32_16x16x32_bf16 v[10:13], v[32:35], v[96:99], 0
	s_waitcnt vmcnt(14)
	v_mfma_f32_16x16x32_bf16 v[10:13], v[36:39], v[100:103], v[10:13]
	s_waitcnt vmcnt(13)
	v_mfma_f32_16x16x32_bf16 v[10:13], v[40:43], v[104:107], v[10:13]
	s_waitcnt vmcnt(12)
	v_mfma_f32_16x16x32_bf16 v[10:13], v[44:47], v[108:111], v[10:13]
	s_waitcnt vmcnt(11)
	v_mfma_f32_16x16x32_bf16 v[10:13], v[48:51], v[112:115], v[10:13]
	s_waitcnt vmcnt(10)
	v_mfma_f32_16x16x32_bf16 v[10:13], v[52:55], v[116:119], v[10:13]
	s_waitcnt vmcnt(9)
	v_mfma_f32_16x16x32_bf16 v[10:13], v[56:59], v[120:123], v[10:13]
	s_waitcnt vmcnt(8)
	v_mfma_f32_16x16x32_bf16 v[10:13], v[60:63], v[124:127], v[10:13]
	s_waitcnt vmcnt(7)
	v_mfma_f32_16x16x32_bf16 v[10:13], v[64:67], v[128:131], v[10:13]
	s_waitcnt vmcnt(6)
	v_mfma_f32_16x16x32_bf16 v[10:13], v[68:71], v[132:135], v[10:13]
	s_waitcnt vmcnt(5)
	v_mfma_f32_16x16x32_bf16 v[10:13], v[72:75], v[136:139], v[10:13]
	s_waitcnt vmcnt(4)
	v_mfma_f32_16x16x32_bf16 v[10:13], v[76:79], v[140:143], v[10:13]
	s_waitcnt vmcnt(3)
	v_mfma_f32_16x16x32_bf16 v[10:13], v[80:83], v[144:147], v[10:13]
	s_waitcnt vmcnt(2)
	v_mfma_f32_16x16x32_bf16 v[10:13], v[84:87], v[148:151], v[10:13]
	s_waitcnt vmcnt(1)
	v_mfma_f32_16x16x32_bf16 v[10:13], v[88:91], v[152:155], v[10:13]
	s_waitcnt vmcnt(0)
	v_mfma_f32_16x16x32_bf16 v[10:13], v[92:95], v[156:159], v[10:13]
	s_nop 7
	ds_write2_b32 v9, v10, v11 offset1:16
	ds_write2_b32 v9, v12, v13 offset0:32 offset1:48
	s_waitcnt lgkmcnt(0)
	s_barrier
	ds_read2st64_b32 v[10:11], v8 offset1:4
	s_waitcnt lgkmcnt(0)
	v_add_f32_e32 v7, v10, v11
	ds_read2st64_b32 v[10:11], v8 offset0:8 offset1:12
	s_waitcnt lgkmcnt(0)
	v_add_f32_e32 v7, v7, v10
	v_add_f32_e32 v7, v7, v11
	global_store_dword v[4:5], v7, off
	v_lshl_add_u64 v[4:5], v[4:5], 0, s[30:31]
	s_cbranch_scc0 .LBB0_247
